# v39: v36 + epilogue priority hand-off: waves 0-3 (leading half) at s_setprio 1 from each GEMM K-loop exit through epilogue and next-unit preamble, s_setprio 0 at every K-loop entry
# baseline (speedup 1.0000x reference)
.LBB0_229:
	s_ashr_i32 s57, s56, 31
	s_lshl_b64 s[30:31], s[56:57], 21
	s_add_u32 s24, s36, s30
	v_readlane_b32 s20, v254, 7
	s_addc_u32 s25, s20, s31
	s_and_b64 s[30:31], s[88:89], exec
	s_cselect_b32 s34, s25, s1
	s_cselect_b32 s35, s24, s0
	s_ashr_i32 s27, s26, 31
	s_lshl_b64 s[30:31], s[26:27], 21
	v_readlane_b32 s20, v254, 2
	s_add_u32 s20, s20, s30
	v_readlane_b32 s21, v254, 3
	s_addc_u32 s21, s21, s31
	s_and_b64 s[30:31], s[88:89], exec
	s_cselect_b32 s27, s21, s29
	s_cselect_b32 s40, s20, s28
	s_add_u32 s0, s0, 0x100080
	s_addc_u32 s1, s1, 0
	s_add_u32 s41, s28, 0x100
	v_mov_b64_e32 v[2:3], 0
	v_mov_b64_e32 v[4:5], 0
	v_mov_b64_e32 v[6:7], 0
	v_mov_b64_e32 v[8:9], 0
	v_mov_b64_e32 v[10:11], 0
	v_mov_b64_e32 v[12:13], 0
	v_mov_b64_e32 v[14:15], 0
	v_mov_b64_e32 v[16:17], 0
	v_mov_b64_e32 v[18:19], 0
	v_mov_b64_e32 v[20:21], 0
	v_mov_b64_e32 v[22:23], 0
	v_mov_b64_e32 v[24:25], 0
	v_mov_b64_e32 v[26:27], 0
	v_mov_b64_e32 v[28:29], 0
	v_mov_b64_e32 v[30:31], 0
	v_mov_b64_e32 v[32:33], 0
	v_mov_b64_e32 v[34:35], 0
	v_mov_b64_e32 v[36:37], 0
	v_mov_b64_e32 v[38:39], 0
	v_mov_b64_e32 v[40:41], 0
	v_mov_b64_e32 v[42:43], 0
	v_mov_b64_e32 v[44:45], 0
	v_mov_b64_e32 v[46:47], 0
	v_mov_b64_e32 v[48:49], 0
	v_mov_b64_e32 v[50:51], 0
	v_mov_b64_e32 v[52:53], 0
	v_mov_b64_e32 v[54:55], 0
	v_mov_b64_e32 v[56:57], 0
	v_mov_b64_e32 v[58:59], 0
	v_mov_b64_e32 v[60:61], 0
	v_mov_b64_e32 v[62:63], 0
	v_mov_b64_e32 v[64:65], 0
	v_mov_b64_e32 v[66:67], 0
	v_mov_b64_e32 v[68:69], 0
	v_mov_b64_e32 v[70:71], 0
	v_mov_b64_e32 v[72:73], 0
	v_mov_b64_e32 v[74:75], 0
	v_mov_b64_e32 v[76:77], 0
	v_mov_b64_e32 v[78:79], 0
	v_mov_b64_e32 v[80:81], 0
	v_mov_b64_e32 v[82:83], 0
	v_mov_b64_e32 v[84:85], 0
	v_mov_b64_e32 v[86:87], 0
	v_mov_b64_e32 v[88:89], 0
	v_mov_b64_e32 v[90:91], 0
	v_mov_b64_e32 v[92:93], 0
	v_mov_b64_e32 v[94:95], 0
	v_mov_b64_e32 v[96:97], 0
	v_mov_b64_e32 v[98:99], 0
	v_mov_b64_e32 v[100:101], 0
	v_mov_b64_e32 v[102:103], 0
	v_mov_b64_e32 v[104:105], 0
	v_mov_b64_e32 v[106:107], 0
	v_mov_b64_e32 v[108:109], 0
	v_mov_b64_e32 v[110:111], 0
	v_mov_b64_e32 v[112:113], 0
	v_mov_b64_e32 v[114:115], 0
	v_mov_b64_e32 v[116:117], 0
	v_mov_b64_e32 v[118:119], 0
	v_mov_b64_e32 v[120:121], 0
	v_mov_b64_e32 v[122:123], 0
	v_mov_b64_e32 v[124:125], 0
	v_mov_b64_e32 v[126:127], 0
	v_mov_b64_e32 v[128:129], 0
	s_addc_u32 s43, s29, 0
	s_mov_b32 s50, -2
	s_setprio 0
.LBB0_230:
	s_add_u32 s98, s0, 0xfff00000
	s_addc_u32 s99, s1, -1
	s_add_u32 s28, s0, 0xfff00080
	s_addc_u32 s29, s1, -1
	s_add_i32 s51, 0, 0x10000
	s_cmp_eq_u32 s50, 60
	s_cselect_b32 s31, s34, s29
	s_cselect_b32 s30, s35, s28
	v_add_u32_e32 v0, s51, v179
	s_cselect_b32 s29, s27, s43
	s_cselect_b32 s28, s40, s41
	s_add_i32 s77, 0, 0x14000
	ds_read_b128 v[130:133], v0
	ds_read_b128 v[134:137], v0 offset:1024
	ds_read_b128 v[138:141], v0 offset:2048
	ds_read_b128 v[142:145], v0 offset:3072
	v_add_u32_e32 v0, s77, v179
	ds_read_b128 v[146:149], v0
	ds_read_b128 v[150:153], v0 offset:1024
	ds_read_b128 v[154:157], v0 offset:2048
	ds_read_b128 v[158:161], v0 offset:3072
	s_mov_b32 m0, s54
	ds_read_b128 v[174:177], v192
	ds_read_b128 v[180:183], v192 offset:1024
	ds_read_b128 v[184:187], v192 offset:2048
	ds_read_b128 v[188:191], v192 offset:3072
	ds_read_b128 v[200:203], v192 offset:4096
	ds_read_b128 v[204:207], v192 offset:5120
	ds_read_b128 v[208:211], v192 offset:6144
	ds_read_b128 v[212:215], v192 offset:7168
	global_load_lds_dwordx4 v168, s[98:99]
	s_mov_b32 m0, s55
	s_nop 0
	global_load_lds_dwordx4 v164, s[98:99]
	s_add_i32 m0, s14, 0xc000
	s_nop 0
	global_load_lds_dwordx4 v170, s[0:1]
	s_add_i32 m0, s14, 0xe000
	s_nop 0
	global_load_lds_dwordx4 v172, s[0:1]
	s_waitcnt vmcnt(8)
	s_waitcnt lgkmcnt(0)
	s_barrier
	s_waitcnt lgkmcnt(0)
	v_mfma_f32_16x16x32_bf16 v[126:129], v[130:133], v[174:177], v[126:129]
	v_mfma_f32_16x16x32_bf16 v[126:129], v[134:137], v[180:183], v[126:129]
	v_mfma_f32_16x16x32_bf16 v[110:113], v[130:133], v[184:187], v[110:113]
	v_mfma_f32_16x16x32_bf16 v[110:113], v[134:137], v[188:191], v[110:113]
	v_mfma_f32_16x16x32_bf16 v[94:97], v[130:133], v[200:203], v[94:97]
	v_mfma_f32_16x16x32_bf16 v[94:97], v[134:137], v[204:207], v[94:97]
	v_mfma_f32_16x16x32_bf16 v[78:81], v[130:133], v[208:211], v[78:81]
	v_mfma_f32_16x16x32_bf16 v[78:81], v[134:137], v[212:215], v[78:81]
	v_mfma_f32_16x16x32_bf16 v[122:125], v[138:141], v[174:177], v[122:125]
	v_mfma_f32_16x16x32_bf16 v[122:125], v[142:145], v[180:183], v[122:125]
	v_mfma_f32_16x16x32_bf16 v[106:109], v[138:141], v[184:187], v[106:109]
	v_mfma_f32_16x16x32_bf16 v[106:109], v[142:145], v[188:191], v[106:109]
	v_mfma_f32_16x16x32_bf16 v[90:93], v[138:141], v[200:203], v[90:93]
	v_mfma_f32_16x16x32_bf16 v[90:93], v[142:145], v[204:207], v[90:93]
	v_mfma_f32_16x16x32_bf16 v[74:77], v[138:141], v[208:211], v[74:77]
	v_mfma_f32_16x16x32_bf16 v[74:77], v[142:145], v[212:215], v[74:77]
	v_mfma_f32_16x16x32_bf16 v[118:121], v[146:149], v[174:177], v[118:121]
	v_mfma_f32_16x16x32_bf16 v[118:121], v[150:153], v[180:183], v[118:121]
	v_mfma_f32_16x16x32_bf16 v[102:105], v[146:149], v[184:187], v[102:105]
	v_mfma_f32_16x16x32_bf16 v[102:105], v[150:153], v[188:191], v[102:105]
	v_mfma_f32_16x16x32_bf16 v[86:89], v[146:149], v[200:203], v[86:89]
	v_mfma_f32_16x16x32_bf16 v[86:89], v[150:153], v[204:207], v[86:89]
	v_mfma_f32_16x16x32_bf16 v[70:73], v[146:149], v[208:211], v[70:73]
	v_mfma_f32_16x16x32_bf16 v[70:73], v[150:153], v[212:215], v[70:73]
	v_mfma_f32_16x16x32_bf16 v[114:117], v[154:157], v[174:177], v[114:117]
	v_mfma_f32_16x16x32_bf16 v[114:117], v[158:161], v[180:183], v[114:117]
	v_mfma_f32_16x16x32_bf16 v[98:101], v[154:157], v[184:187], v[98:101]
	v_mfma_f32_16x16x32_bf16 v[98:101], v[158:161], v[188:191], v[98:101]
	v_mfma_f32_16x16x32_bf16 v[82:85], v[154:157], v[200:203], v[82:85]
	v_mfma_f32_16x16x32_bf16 v[82:85], v[158:161], v[204:207], v[82:85]
	v_mfma_f32_16x16x32_bf16 v[66:69], v[154:157], v[208:211], v[66:69]
	v_mfma_f32_16x16x32_bf16 v[66:69], v[158:161], v[212:215], v[66:69]
	s_barrier
	s_add_i32 s51, s51, s9
	s_mov_b32 m0, s51
	ds_read_b128 v[174:177], v192 offset:16384
	ds_read_b128 v[180:183], v192 offset:17408
	ds_read_b128 v[184:187], v192 offset:18432
	ds_read_b128 v[188:191], v192 offset:19456
	ds_read_b128 v[200:203], v192 offset:20480
	ds_read_b128 v[204:207], v192 offset:21504
	ds_read_b128 v[208:211], v192 offset:22528
	ds_read_b128 v[212:215], v192 offset:23552
	global_load_lds_dwordx4 v166, s[28:29]
	s_add_i32 m0, s51, 0x2000
	s_add_u32 s80, s28, 0x100000
	s_addc_u32 s81, s29, 0
	s_add_i32 s51, s77, s9
	global_load_lds_dwordx4 v162, s[28:29]
	s_mov_b32 m0, s51
	s_nop 0
	global_load_lds_dwordx4 v166, s[80:81]
	s_add_i32 m0, s51, 0x2000
	s_nop 0
	global_load_lds_dwordx4 v162, s[80:81]
	s_waitcnt vmcnt(6)
	s_waitcnt lgkmcnt(0)
	s_barrier
	s_waitcnt lgkmcnt(0)
	v_mfma_f32_16x16x32_bf16 v[62:65], v[130:133], v[174:177], v[62:65]
	v_mfma_f32_16x16x32_bf16 v[62:65], v[134:137], v[180:183], v[62:65]
	v_mfma_f32_16x16x32_bf16 v[46:49], v[130:133], v[184:187], v[46:49]
	v_mfma_f32_16x16x32_bf16 v[46:49], v[134:137], v[188:191], v[46:49]
	v_mfma_f32_16x16x32_bf16 v[30:33], v[130:133], v[200:203], v[30:33]
	v_mfma_f32_16x16x32_bf16 v[30:33], v[134:137], v[204:207], v[30:33]
	v_mfma_f32_16x16x32_bf16 v[14:17], v[130:133], v[208:211], v[14:17]
	v_mfma_f32_16x16x32_bf16 v[14:17], v[134:137], v[212:215], v[14:17]
	v_mfma_f32_16x16x32_bf16 v[58:61], v[138:141], v[174:177], v[58:61]
	v_mfma_f32_16x16x32_bf16 v[58:61], v[142:145], v[180:183], v[58:61]
	v_mfma_f32_16x16x32_bf16 v[42:45], v[138:141], v[184:187], v[42:45]
	v_mfma_f32_16x16x32_bf16 v[42:45], v[142:145], v[188:191], v[42:45]
	v_mfma_f32_16x16x32_bf16 v[26:29], v[138:141], v[200:203], v[26:29]
	v_mfma_f32_16x16x32_bf16 v[26:29], v[142:145], v[204:207], v[26:29]
	v_mfma_f32_16x16x32_bf16 v[10:13], v[138:141], v[208:211], v[10:13]
	v_mfma_f32_16x16x32_bf16 v[10:13], v[142:145], v[212:215], v[10:13]
	v_mfma_f32_16x16x32_bf16 v[54:57], v[146:149], v[174:177], v[54:57]
	v_mfma_f32_16x16x32_bf16 v[54:57], v[150:153], v[180:183], v[54:57]
	v_mfma_f32_16x16x32_bf16 v[38:41], v[146:149], v[184:187], v[38:41]
	v_mfma_f32_16x16x32_bf16 v[38:41], v[150:153], v[188:191], v[38:41]
	v_mfma_f32_16x16x32_bf16 v[22:25], v[146:149], v[200:203], v[22:25]
	v_mfma_f32_16x16x32_bf16 v[22:25], v[150:153], v[204:207], v[22:25]
	v_mfma_f32_16x16x32_bf16 v[6:9], v[146:149], v[208:211], v[6:9]
	v_mfma_f32_16x16x32_bf16 v[6:9], v[150:153], v[212:215], v[6:9]
	v_mfma_f32_16x16x32_bf16 v[50:53], v[154:157], v[174:177], v[50:53]
	v_mfma_f32_16x16x32_bf16 v[50:53], v[158:161], v[180:183], v[50:53]
	v_mfma_f32_16x16x32_bf16 v[34:37], v[154:157], v[184:187], v[34:37]
	v_mfma_f32_16x16x32_bf16 v[34:37], v[158:161], v[188:191], v[34:37]
	v_mfma_f32_16x16x32_bf16 v[18:21], v[154:157], v[200:203], v[18:21]
	v_mfma_f32_16x16x32_bf16 v[18:21], v[158:161], v[204:207], v[18:21]
	v_mfma_f32_16x16x32_bf16 v[2:5], v[154:157], v[208:211], v[2:5]
	v_mfma_f32_16x16x32_bf16 v[2:5], v[158:161], v[212:215], v[2:5]
	s_barrier
	s_add_i32 s51, 0, 0x18000
	v_add_u32_e32 v0, s51, v179
	s_add_i32 s77, 0, 0x1c000
	ds_read_b128 v[130:133], v0
	ds_read_b128 v[134:137], v0 offset:1024
	ds_read_b128 v[138:141], v0 offset:2048
	ds_read_b128 v[142:145], v0 offset:3072
	v_add_u32_e32 v0, s77, v179
	ds_read_b128 v[146:149], v0
	ds_read_b128 v[150:153], v0 offset:1024
	ds_read_b128 v[154:157], v0 offset:2048
	ds_read_b128 v[158:161], v0 offset:3072
	s_mov_b32 m0, s14
	ds_read_b128 v[174:177], v192 offset:32768
	ds_read_b128 v[180:183], v192 offset:33792
	ds_read_b128 v[184:187], v192 offset:34816
	ds_read_b128 v[188:191], v192 offset:35840
	ds_read_b128 v[200:203], v192 offset:36864
	ds_read_b128 v[204:207], v192 offset:37888
	ds_read_b128 v[208:211], v192 offset:38912
	ds_read_b128 v[212:215], v192 offset:39936
	global_load_lds_dwordx4 v168, s[30:31]
	s_mov_b32 m0, s15
	s_nop 0
	global_load_lds_dwordx4 v164, s[30:31]
	s_add_u32 s30, s30, 0x100000
	s_addc_u32 s31, s31, 0
	s_mov_b32 m0, s52
	s_nop 0
	global_load_lds_dwordx4 v168, s[30:31]
	s_mov_b32 m0, s53
	s_nop 0
	global_load_lds_dwordx4 v164, s[30:31]
	s_waitcnt vmcnt(8)
	s_waitcnt lgkmcnt(0)
	s_barrier
	s_waitcnt lgkmcnt(0)
	v_mfma_f32_16x16x32_bf16 v[126:129], v[130:133], v[174:177], v[126:129]
	v_mfma_f32_16x16x32_bf16 v[126:129], v[134:137], v[180:183], v[126:129]
	v_mfma_f32_16x16x32_bf16 v[110:113], v[130:133], v[184:187], v[110:113]
	v_mfma_f32_16x16x32_bf16 v[110:113], v[134:137], v[188:191], v[110:113]
	v_mfma_f32_16x16x32_bf16 v[94:97], v[130:133], v[200:203], v[94:97]
	v_mfma_f32_16x16x32_bf16 v[94:97], v[134:137], v[204:207], v[94:97]
	v_mfma_f32_16x16x32_bf16 v[78:81], v[130:133], v[208:211], v[78:81]
	v_mfma_f32_16x16x32_bf16 v[78:81], v[134:137], v[212:215], v[78:81]
	v_mfma_f32_16x16x32_bf16 v[122:125], v[138:141], v[174:177], v[122:125]
	v_mfma_f32_16x16x32_bf16 v[122:125], v[142:145], v[180:183], v[122:125]
	v_mfma_f32_16x16x32_bf16 v[106:109], v[138:141], v[184:187], v[106:109]
	v_mfma_f32_16x16x32_bf16 v[106:109], v[142:145], v[188:191], v[106:109]
	v_mfma_f32_16x16x32_bf16 v[90:93], v[138:141], v[200:203], v[90:93]
	v_mfma_f32_16x16x32_bf16 v[90:93], v[142:145], v[204:207], v[90:93]
	v_mfma_f32_16x16x32_bf16 v[74:77], v[138:141], v[208:211], v[74:77]
	v_mfma_f32_16x16x32_bf16 v[74:77], v[142:145], v[212:215], v[74:77]
	v_mfma_f32_16x16x32_bf16 v[118:121], v[146:149], v[174:177], v[118:121]
	v_mfma_f32_16x16x32_bf16 v[118:121], v[150:153], v[180:183], v[118:121]
	v_mfma_f32_16x16x32_bf16 v[102:105], v[146:149], v[184:187], v[102:105]
	v_mfma_f32_16x16x32_bf16 v[102:105], v[150:153], v[188:191], v[102:105]
	v_mfma_f32_16x16x32_bf16 v[86:89], v[146:149], v[200:203], v[86:89]
	v_mfma_f32_16x16x32_bf16 v[86:89], v[150:153], v[204:207], v[86:89]
	v_mfma_f32_16x16x32_bf16 v[70:73], v[146:149], v[208:211], v[70:73]
	v_mfma_f32_16x16x32_bf16 v[70:73], v[150:153], v[212:215], v[70:73]
	v_mfma_f32_16x16x32_bf16 v[114:117], v[154:157], v[174:177], v[114:117]
	v_mfma_f32_16x16x32_bf16 v[114:117], v[158:161], v[180:183], v[114:117]
	v_mfma_f32_16x16x32_bf16 v[98:101], v[154:157], v[184:187], v[98:101]
	v_mfma_f32_16x16x32_bf16 v[98:101], v[158:161], v[188:191], v[98:101]
	v_mfma_f32_16x16x32_bf16 v[82:85], v[154:157], v[200:203], v[82:85]
	v_mfma_f32_16x16x32_bf16 v[82:85], v[158:161], v[204:207], v[82:85]
	v_mfma_f32_16x16x32_bf16 v[66:69], v[154:157], v[208:211], v[66:69]
	v_mfma_f32_16x16x32_bf16 v[66:69], v[158:161], v[212:215], v[66:69]
	s_barrier
	s_add_u32 s98, s28, 0x80
	s_addc_u32 s99, s29, 0
	s_add_i32 s30, s51, s9
	s_mov_b32 m0, s30
	ds_read_b128 v[174:177], v192 offset:49152
	ds_read_b128 v[180:183], v192 offset:50176
	ds_read_b128 v[184:187], v192 offset:51200
	ds_read_b128 v[188:191], v192 offset:52224
	ds_read_b128 v[200:203], v192 offset:53248
	ds_read_b128 v[204:207], v192 offset:54272
	ds_read_b128 v[208:211], v192 offset:55296
	ds_read_b128 v[212:215], v192 offset:56320
	global_load_lds_dwordx4 v166, s[98:99]
	s_add_i32 m0, s30, 0x2000
	s_add_u32 s28, s28, 0x100080
	s_addc_u32 s29, s29, 0
	s_add_i32 s30, s77, s9
	global_load_lds_dwordx4 v162, s[98:99]
	s_mov_b32 m0, s30
	s_nop 0
	global_load_lds_dwordx4 v166, s[28:29]
	s_add_i32 m0, s30, 0x2000
	s_nop 0
	global_load_lds_dwordx4 v162, s[28:29]
	s_waitcnt vmcnt(6)
	s_waitcnt lgkmcnt(0)
	s_barrier
	s_waitcnt lgkmcnt(0)
	v_mfma_f32_16x16x32_bf16 v[62:65], v[130:133], v[174:177], v[62:65]
	v_mfma_f32_16x16x32_bf16 v[62:65], v[134:137], v[180:183], v[62:65]
	v_mfma_f32_16x16x32_bf16 v[46:49], v[130:133], v[184:187], v[46:49]
	v_mfma_f32_16x16x32_bf16 v[46:49], v[134:137], v[188:191], v[46:49]
	v_mfma_f32_16x16x32_bf16 v[30:33], v[130:133], v[200:203], v[30:33]
	v_mfma_f32_16x16x32_bf16 v[30:33], v[134:137], v[204:207], v[30:33]
	v_mfma_f32_16x16x32_bf16 v[14:17], v[130:133], v[208:211], v[14:17]
	v_mfma_f32_16x16x32_bf16 v[14:17], v[134:137], v[212:215], v[14:17]
	v_mfma_f32_16x16x32_bf16 v[58:61], v[138:141], v[174:177], v[58:61]
	v_mfma_f32_16x16x32_bf16 v[58:61], v[142:145], v[180:183], v[58:61]
	v_mfma_f32_16x16x32_bf16 v[42:45], v[138:141], v[184:187], v[42:45]
	v_mfma_f32_16x16x32_bf16 v[42:45], v[142:145], v[188:191], v[42:45]
	v_mfma_f32_16x16x32_bf16 v[26:29], v[138:141], v[200:203], v[26:29]
	v_mfma_f32_16x16x32_bf16 v[26:29], v[142:145], v[204:207], v[26:29]
	v_mfma_f32_16x16x32_bf16 v[10:13], v[138:141], v[208:211], v[10:13]
	v_mfma_f32_16x16x32_bf16 v[10:13], v[142:145], v[212:215], v[10:13]
	v_mfma_f32_16x16x32_bf16 v[54:57], v[146:149], v[174:177], v[54:57]
	v_mfma_f32_16x16x32_bf16 v[54:57], v[150:153], v[180:183], v[54:57]
	v_mfma_f32_16x16x32_bf16 v[38:41], v[146:149], v[184:187], v[38:41]
	v_mfma_f32_16x16x32_bf16 v[38:41], v[150:153], v[188:191], v[38:41]
	v_mfma_f32_16x16x32_bf16 v[22:25], v[146:149], v[200:203], v[22:25]
	v_mfma_f32_16x16x32_bf16 v[22:25], v[150:153], v[204:207], v[22:25]
	v_mfma_f32_16x16x32_bf16 v[6:9], v[146:149], v[208:211], v[6:9]
	v_mfma_f32_16x16x32_bf16 v[6:9], v[150:153], v[212:215], v[6:9]
	v_mfma_f32_16x16x32_bf16 v[50:53], v[154:157], v[174:177], v[50:53]
	v_mfma_f32_16x16x32_bf16 v[50:53], v[158:161], v[180:183], v[50:53]
	v_mfma_f32_16x16x32_bf16 v[34:37], v[154:157], v[184:187], v[34:37]
	v_mfma_f32_16x16x32_bf16 v[34:37], v[158:161], v[188:191], v[34:37]
	v_mfma_f32_16x16x32_bf16 v[18:21], v[154:157], v[200:203], v[18:21]
	v_mfma_f32_16x16x32_bf16 v[18:21], v[158:161], v[204:207], v[18:21]
	v_mfma_f32_16x16x32_bf16 v[2:5], v[154:157], v[208:211], v[2:5]
	v_mfma_f32_16x16x32_bf16 v[2:5], v[158:161], v[212:215], v[2:5]
	s_barrier
	s_add_i32 s50, s50, 2
	s_add_u32 s0, s0, 0x100
	s_addc_u32 s1, s1, 0
	s_add_u32 s41, s41, 0x100
	s_addc_u32 s43, s43, 0
	s_cmp_gt_u32 s50, 61
	s_cbranch_scc0 .LBB0_230
	s_bitcmp1_b32 s60, 8
	s_cbranch_scc1 .Lepiprio_0
	s_setprio 1
.Lepiprio_0:
	s_and_b64 vcc, exec, s[22:23]
	s_cbranch_vccz .LBB0_233
	s_barrier

.LBB0_299:
	s_ashr_i32 s49, s48, 31
	s_lshl_b64 s[18:19], s[48:49], 20
	s_add_u32 s22, s92, s18
	v_readlane_b32 s18, v251, 32
	s_addc_u32 s23, s18, s19
	s_and_b64 s[18:19], s[38:39], exec
	s_cselect_b32 s18, s23, s1
	s_cselect_b32 s19, s22, s0
	s_ashr_i32 s27, s26, 31
	s_lshl_b64 s[24:25], s[26:27], 20
	s_add_u32 s24, s80, s24
	s_addc_u32 s25, s33, s25
	s_and_b64 s[30:31], s[38:39], exec
	s_cselect_b32 s27, s25, s29
	s_cselect_b32 s34, s24, s28
	s_add_u32 s0, s0, 0x80080
	s_addc_u32 s1, s1, 0
	s_add_u32 s35, s28, 0x100
	v_mov_b64_e32 v[18:19], 0
	v_mov_b64_e32 v[20:21], 0
	v_mov_b64_e32 v[22:23], 0
	v_mov_b64_e32 v[24:25], 0
	v_mov_b64_e32 v[26:27], 0
	v_mov_b64_e32 v[28:29], 0
	v_mov_b64_e32 v[30:31], 0
	v_mov_b64_e32 v[32:33], 0
	v_mov_b64_e32 v[34:35], 0
	v_mov_b64_e32 v[36:37], 0
	v_mov_b64_e32 v[38:39], 0
	v_mov_b64_e32 v[40:41], 0
	v_mov_b64_e32 v[42:43], 0
	v_mov_b64_e32 v[44:45], 0
	v_mov_b64_e32 v[46:47], 0
	v_mov_b64_e32 v[48:49], 0
	v_mov_b64_e32 v[50:51], 0
	v_mov_b64_e32 v[52:53], 0
	v_mov_b64_e32 v[54:55], 0
	v_mov_b64_e32 v[56:57], 0
	v_mov_b64_e32 v[58:59], 0
	v_mov_b64_e32 v[60:61], 0
	v_mov_b64_e32 v[62:63], 0
	v_mov_b64_e32 v[64:65], 0
	v_mov_b64_e32 v[66:67], 0
	v_mov_b64_e32 v[68:69], 0
	v_mov_b64_e32 v[70:71], 0
	v_mov_b64_e32 v[72:73], 0
	v_mov_b64_e32 v[74:75], 0
	v_mov_b64_e32 v[76:77], 0
	v_mov_b64_e32 v[78:79], 0
	v_mov_b64_e32 v[80:81], 0
	v_mov_b64_e32 v[82:83], 0
	v_mov_b64_e32 v[84:85], 0
	v_mov_b64_e32 v[86:87], 0
	v_mov_b64_e32 v[88:89], 0
	v_mov_b64_e32 v[90:91], 0
	v_mov_b64_e32 v[92:93], 0
	v_mov_b64_e32 v[94:95], 0
	v_mov_b64_e32 v[96:97], 0
	v_mov_b64_e32 v[98:99], 0
	v_mov_b64_e32 v[100:101], 0
	v_mov_b64_e32 v[102:103], 0
	v_mov_b64_e32 v[104:105], 0
	v_mov_b64_e32 v[106:107], 0
	v_mov_b64_e32 v[108:109], 0
	v_mov_b64_e32 v[110:111], 0
	v_mov_b64_e32 v[112:113], 0
	v_mov_b64_e32 v[114:115], 0
	v_mov_b64_e32 v[116:117], 0
	v_mov_b64_e32 v[118:119], 0
	v_mov_b64_e32 v[120:121], 0
	v_mov_b64_e32 v[122:123], 0
	v_mov_b64_e32 v[124:125], 0
	v_mov_b64_e32 v[126:127], 0
	v_mov_b64_e32 v[128:129], 0
	v_mov_b64_e32 v[130:131], 0
	v_mov_b64_e32 v[132:133], 0
	v_mov_b64_e32 v[134:135], 0
	v_mov_b64_e32 v[136:137], 0
	v_mov_b64_e32 v[138:139], 0
	v_mov_b64_e32 v[140:141], 0
	v_mov_b64_e32 v[142:143], 0
	v_mov_b64_e32 v[144:145], 0
	s_addc_u32 s40, s29, 0
	s_mov_b32 s41, -2
	s_setprio 0

.Lspf_j2:
	s_waitcnt lgkmcnt(0)
	s_barrier
	s_waitcnt lgkmcnt(0)
	v_mfma_i32_16x16x64_i8 v[142:145], v[34:37], v[174:177], v[142:145]
	v_mfma_i32_16x16x64_i8 v[142:145], v[38:41], v[178:181], v[142:145]
	v_mfma_i32_16x16x64_i8 v[134:137], v[34:37], v[182:185], v[134:137]
	v_mfma_i32_16x16x64_i8 v[134:137], v[38:41], v[186:189], v[134:137]
	v_mfma_i32_16x16x64_i8 v[122:125], v[34:37], v[190:193], v[122:125]
	v_mfma_i32_16x16x64_i8 v[122:125], v[38:41], v[200:203], v[122:125]
	v_mfma_i32_16x16x64_i8 v[106:109], v[34:37], v[204:207], v[106:109]
	v_mfma_i32_16x16x64_i8 v[106:109], v[38:41], v[208:211], v[106:109]
	v_mfma_i32_16x16x64_i8 v[138:141], v[58:61], v[174:177], v[138:141]
	v_mfma_i32_16x16x64_i8 v[138:141], v[62:65], v[178:181], v[138:141]
	v_mfma_i32_16x16x64_i8 v[130:133], v[58:61], v[182:185], v[130:133]
	v_mfma_i32_16x16x64_i8 v[130:133], v[62:65], v[186:189], v[130:133]
	v_mfma_i32_16x16x64_i8 v[114:117], v[58:61], v[190:193], v[114:117]
	v_mfma_i32_16x16x64_i8 v[114:117], v[62:65], v[200:203], v[114:117]
	v_mfma_i32_16x16x64_i8 v[98:101], v[58:61], v[204:207], v[98:101]
	v_mfma_i32_16x16x64_i8 v[98:101], v[62:65], v[208:211], v[98:101]
	v_mfma_i32_16x16x64_i8 v[126:129], v[146:149], v[174:177], v[126:129]
	v_mfma_i32_16x16x64_i8 v[126:129], v[150:153], v[178:181], v[126:129]
	v_mfma_i32_16x16x64_i8 v[110:113], v[146:149], v[182:185], v[110:113]
	v_mfma_i32_16x16x64_i8 v[110:113], v[150:153], v[186:189], v[110:113]
	v_mfma_i32_16x16x64_i8 v[94:97], v[146:149], v[190:193], v[94:97]
	v_mfma_i32_16x16x64_i8 v[94:97], v[150:153], v[200:203], v[94:97]
	v_mfma_i32_16x16x64_i8 v[86:89], v[146:149], v[204:207], v[86:89]
	v_mfma_i32_16x16x64_i8 v[86:89], v[150:153], v[208:211], v[86:89]
	v_mfma_i32_16x16x64_i8 v[118:121], v[154:157], v[174:177], v[118:121]
	v_mfma_i32_16x16x64_i8 v[118:121], v[158:161], v[178:181], v[118:121]
	v_mfma_i32_16x16x64_i8 v[102:105], v[154:157], v[182:185], v[102:105]
	v_mfma_i32_16x16x64_i8 v[102:105], v[158:161], v[186:189], v[102:105]
	v_mfma_i32_16x16x64_i8 v[90:93], v[154:157], v[190:193], v[90:93]
	v_mfma_i32_16x16x64_i8 v[90:93], v[158:161], v[200:203], v[90:93]
	v_mfma_i32_16x16x64_i8 v[82:85], v[154:157], v[204:207], v[82:85]
	v_mfma_i32_16x16x64_i8 v[82:85], v[158:161], v[208:211], v[82:85]
	s_barrier
	s_add_i32 s30, s42, s81
	s_add_u32 s98, s28, 0x80
	s_addc_u32 s99, s29, 0
	s_mov_b32 m0, s30
	ds_read_b128 v[174:177], v250 offset:49152
	ds_read_b128 v[178:181], v250 offset:50176
	ds_read_b128 v[182:185], v250 offset:51200
	ds_read_b128 v[186:189], v250 offset:52224
	ds_read_b128 v[190:193], v250 offset:53248
	ds_read_b128 v[200:203], v250 offset:54272
	ds_read_b128 v[204:207], v250 offset:55296
	ds_read_b128 v[208:211], v250 offset:56320
	global_load_lds_dwordx4 v164, s[98:99]
	s_add_i32 m0, s30, 0x2000
	s_add_u32 s28, s28, 0x80080
	s_addc_u32 s29, s29, 0
	s_add_i32 s30, s43, s81
	global_load_lds_dwordx4 v168, s[98:99]
	s_mov_b32 m0, s30
	s_nop 0
	global_load_lds_dwordx4 v164, s[28:29]
	s_add_i32 m0, s30, 0x2000
	s_nop 0
	global_load_lds_dwordx4 v168, s[28:29]
	s_waitcnt vmcnt(6)
	s_waitcnt lgkmcnt(0)
	s_barrier
	s_waitcnt lgkmcnt(0)
	v_mfma_i32_16x16x64_i8 v[78:81], v[34:37], v[174:177], v[78:81]
	v_mfma_i32_16x16x64_i8 v[78:81], v[38:41], v[178:181], v[78:81]
	v_mfma_i32_16x16x64_i8 v[70:73], v[34:37], v[182:185], v[70:73]
	v_mfma_i32_16x16x64_i8 v[70:73], v[38:41], v[186:189], v[70:73]
	v_mfma_i32_16x16x64_i8 v[54:57], v[34:37], v[190:193], v[54:57]
	v_mfma_i32_16x16x64_i8 v[54:57], v[38:41], v[200:203], v[54:57]
	v_mfma_i32_16x16x64_i8 v[2:5], v[34:37], v[204:207], v[2:5]
	v_mfma_i32_16x16x64_i8 v[38:41], v[38:41], v[208:211], v[2:5]
	v_mfma_i32_16x16x64_i8 v[74:77], v[58:61], v[174:177], v[74:77]
	v_mfma_i32_16x16x64_i8 v[74:77], v[62:65], v[178:181], v[74:77]
	v_mfma_i32_16x16x64_i8 v[66:69], v[58:61], v[182:185], v[66:69]
	v_mfma_i32_16x16x64_i8 v[66:69], v[62:65], v[186:189], v[66:69]
	v_mfma_i32_16x16x64_i8 v[50:53], v[58:61], v[190:193], v[50:53]
	v_mfma_i32_16x16x64_i8 v[50:53], v[62:65], v[200:203], v[50:53]
	v_mfma_i32_16x16x64_i8 v[2:5], v[58:61], v[204:207], v[6:9]
	v_mfma_i32_16x16x64_i8 v[34:37], v[62:65], v[208:211], v[2:5]
	v_mfma_i32_16x16x64_i8 v[2:5], v[146:149], v[174:177], v[10:13]
	v_mfma_i32_16x16x64_i8 v[62:65], v[150:153], v[178:181], v[2:5]
	v_mfma_i32_16x16x64_i8 v[2:5], v[154:157], v[174:177], v[14:17]
	v_mfma_i32_16x16x64_i8 v[58:61], v[158:161], v[178:181], v[2:5]
	v_mfma_i32_16x16x64_i8 v[2:5], v[146:149], v[182:185], v[46:49]
	v_mfma_i32_16x16x64_i8 v[46:49], v[150:153], v[186:189], v[2:5]
	v_mfma_i32_16x16x64_i8 v[2:5], v[154:157], v[182:185], v[42:45]
	v_mfma_i32_16x16x64_i8 v[42:45], v[158:161], v[186:189], v[2:5]
	v_mfma_i32_16x16x64_i8 v[2:5], v[146:149], v[190:193], v[30:33]
	v_mfma_i32_16x16x64_i8 v[30:33], v[150:153], v[200:203], v[2:5]
	v_mfma_i32_16x16x64_i8 v[2:5], v[154:157], v[190:193], v[26:29]
	v_mfma_i32_16x16x64_i8 v[26:29], v[158:161], v[200:203], v[2:5]
	v_mfma_i32_16x16x64_i8 v[2:5], v[146:149], v[204:207], v[22:25]
	v_mfma_i32_16x16x64_i8 v[22:25], v[150:153], v[208:211], v[2:5]
	v_mfma_i32_16x16x64_i8 v[2:5], v[154:157], v[204:207], v[18:21]
	v_mfma_i32_16x16x64_i8 v[18:21], v[158:161], v[208:211], v[2:5]
	s_barrier
	s_add_i32 s41, s41, 2
	s_add_u32 s0, s0, 0x100
	s_addc_u32 s1, s1, 0
	s_add_u32 s35, s35, 0x100
	s_addc_u32 s40, s40, 0
	s_cmp_gt_u32 s41, 29
	s_cbranch_scc0 .LBB0_300
	s_bitcmp1_b32 s60, 8
	s_cbranch_scc1 .Lepiprio_1
	s_setprio 1
.Lepiprio_1:
	s_and_b64 vcc, exec, s[52:53]
	s_cbranch_vccz .LBB0_303
	s_barrier

.LBB0_576:
	s_ashr_i32 s23, s22, 31
	s_lshl_b64 s[26:27], s[22:23], 20
	s_add_u32 s26, s68, s26
	s_addc_u32 s27, s69, s27
	s_and_b64 s[28:29], s[40:41], exec
	s_cselect_b32 s19, s27, s31
	s_cselect_b32 s23, s26, s30
	s_ashr_i32 s25, s24, 31
	s_lshl_b64 s[28:29], s[24:25], 20
	s_add_u32 s28, s9, s28
	s_addc_u32 s29, s14, s29
	s_and_b64 s[42:43], s[40:41], exec
	s_cselect_b32 s25, s29, s35
	s_cselect_b32 s54, s28, s34
	s_add_u32 s30, s30, 0x80080
	s_addc_u32 s31, s31, 0
	s_add_u32 s55, s34, 0x100
	s_addc_u32 s56, s35, 0
	s_mov_b32 s57, -2
	s_setprio 0
.LBB0_577:
	s_add_u32 s98, s30, 0xfff80000
	s_addc_u32 s99, s31, -1
	s_add_u32 s34, s30, 0xfff80080
	s_addc_u32 s35, s31, -1
	s_add_i32 s66, 0, 0x10000
	s_cmp_eq_u32 s57, 28
	s_cselect_b32 s43, s19, s35
	s_cselect_b32 s42, s23, s34
	v_add_u32_e32 v0, s66, v228
	s_cselect_b32 s35, s25, s56
	s_cselect_b32 s34, s54, s55
	s_add_i32 s73, 0, 0x14000
	ds_read_b128 v[132:135], v0
	ds_read_b128 v[136:139], v0 offset:1024
	ds_read_b128 v[140:143], v0 offset:2048
	ds_read_b128 v[144:147], v0 offset:3072
	v_add_u32_e32 v0, s73, v228
	ds_read_b128 v[148:151], v0
	ds_read_b128 v[152:155], v0 offset:1024
	ds_read_b128 v[156:159], v0 offset:2048
	ds_read_b128 v[160:163], v0 offset:3072
	s_mov_b32 m0, s50
	ds_read_b128 v[164:167], v230
	ds_read_b128 v[168:171], v230 offset:1024
	ds_read_b128 v[172:175], v230 offset:2048
	ds_read_b128 v[176:179], v230 offset:3072
	ds_read_b128 v[180:183], v230 offset:4096
	ds_read_b128 v[184:187], v230 offset:5120
	ds_read_b128 v[188:191], v230 offset:6144
	ds_read_b128 v[192:195], v230 offset:7168
	global_load_lds_dwordx4 v206, s[98:99]
	s_mov_b32 m0, s51
	s_nop 0
	global_load_lds_dwordx4 v202, s[98:99]
	s_add_i32 m0, s46, 0xc000
	s_nop 0
	global_load_lds_dwordx4 v208, s[30:31]
	s_add_i32 m0, s46, 0xe000
	s_nop 0
	global_load_lds_dwordx4 v210, s[30:31]
	s_waitcnt vmcnt(8)
	s_waitcnt lgkmcnt(0)
	s_barrier
	s_waitcnt lgkmcnt(0)
	v_mfma_f32_16x16x32_bf16 v[128:131], v[132:135], v[164:167], v[128:131]
	v_mfma_f32_16x16x32_bf16 v[128:131], v[136:139], v[168:171], v[128:131]
	v_mfma_f32_16x16x32_bf16 v[120:123], v[132:135], v[172:175], v[120:123]
	v_mfma_f32_16x16x32_bf16 v[120:123], v[136:139], v[176:179], v[120:123]
	v_mfma_f32_16x16x32_bf16 v[112:115], v[132:135], v[180:183], v[112:115]
	v_mfma_f32_16x16x32_bf16 v[112:115], v[136:139], v[184:187], v[112:115]
	v_mfma_f32_16x16x32_bf16 v[104:107], v[132:135], v[188:191], v[104:107]
	v_mfma_f32_16x16x32_bf16 v[104:107], v[136:139], v[192:195], v[104:107]
	v_mfma_f32_16x16x32_bf16 v[124:127], v[140:143], v[164:167], v[124:127]
	v_mfma_f32_16x16x32_bf16 v[124:127], v[144:147], v[168:171], v[124:127]
	v_mfma_f32_16x16x32_bf16 v[116:119], v[140:143], v[172:175], v[116:119]
	v_mfma_f32_16x16x32_bf16 v[116:119], v[144:147], v[176:179], v[116:119]
	v_mfma_f32_16x16x32_bf16 v[108:111], v[140:143], v[180:183], v[108:111]
	v_mfma_f32_16x16x32_bf16 v[108:111], v[144:147], v[184:187], v[108:111]
	v_mfma_f32_16x16x32_bf16 v[100:103], v[140:143], v[188:191], v[100:103]
	v_mfma_f32_16x16x32_bf16 v[100:103], v[144:147], v[192:195], v[100:103]
	v_mfma_f32_16x16x32_bf16 v[96:99], v[148:151], v[164:167], v[96:99]
	v_mfma_f32_16x16x32_bf16 v[96:99], v[152:155], v[168:171], v[96:99]
	v_mfma_f32_16x16x32_bf16 v[88:91], v[148:151], v[172:175], v[88:91]
	v_mfma_f32_16x16x32_bf16 v[88:91], v[152:155], v[176:179], v[88:91]
	v_mfma_f32_16x16x32_bf16 v[80:83], v[148:151], v[180:183], v[80:83]
	v_mfma_f32_16x16x32_bf16 v[80:83], v[152:155], v[184:187], v[80:83]
	v_mfma_f32_16x16x32_bf16 v[72:75], v[148:151], v[188:191], v[72:75]
	v_mfma_f32_16x16x32_bf16 v[72:75], v[152:155], v[192:195], v[72:75]
	v_mfma_f32_16x16x32_bf16 v[92:95], v[156:159], v[164:167], v[92:95]
	v_mfma_f32_16x16x32_bf16 v[92:95], v[160:163], v[168:171], v[92:95]
	v_mfma_f32_16x16x32_bf16 v[84:87], v[156:159], v[172:175], v[84:87]
	v_mfma_f32_16x16x32_bf16 v[84:87], v[160:163], v[176:179], v[84:87]
	v_mfma_f32_16x16x32_bf16 v[76:79], v[156:159], v[180:183], v[76:79]
	v_mfma_f32_16x16x32_bf16 v[76:79], v[160:163], v[184:187], v[76:79]
	v_mfma_f32_16x16x32_bf16 v[68:71], v[156:159], v[188:191], v[68:71]
	v_mfma_f32_16x16x32_bf16 v[68:71], v[160:163], v[192:195], v[68:71]
	s_barrier
	s_add_i32 s66, s66, s15
	s_mov_b32 m0, s66
	ds_read_b128 v[164:167], v230 offset:16384
	ds_read_b128 v[168:171], v230 offset:17408
	ds_read_b128 v[172:175], v230 offset:18432
	ds_read_b128 v[176:179], v230 offset:19456
	ds_read_b128 v[180:183], v230 offset:20480
	ds_read_b128 v[184:187], v230 offset:21504
	ds_read_b128 v[188:191], v230 offset:22528
	ds_read_b128 v[192:195], v230 offset:23552
	global_load_lds_dwordx4 v204, s[34:35]
	s_add_i32 m0, s66, 0x2000
	s_add_u32 s66, s34, 0x80000
	s_addc_u32 s67, s35, 0
	s_add_i32 s73, s73, s15
	global_load_lds_dwordx4 v200, s[34:35]
	s_mov_b32 m0, s73
	s_nop 0
	global_load_lds_dwordx4 v204, s[66:67]
	s_add_i32 m0, s73, 0x2000
	s_nop 0
	global_load_lds_dwordx4 v200, s[66:67]
	s_waitcnt vmcnt(6)
	s_waitcnt lgkmcnt(0)
	s_barrier
	s_waitcnt lgkmcnt(0)
	v_mfma_f32_16x16x32_bf16 v[64:67], v[132:135], v[164:167], v[64:67]
	v_mfma_f32_16x16x32_bf16 v[64:67], v[136:139], v[168:171], v[64:67]
	v_mfma_f32_16x16x32_bf16 v[56:59], v[132:135], v[172:175], v[56:59]
	v_mfma_f32_16x16x32_bf16 v[56:59], v[136:139], v[176:179], v[56:59]
	v_mfma_f32_16x16x32_bf16 v[48:51], v[132:135], v[180:183], v[48:51]
	v_mfma_f32_16x16x32_bf16 v[48:51], v[136:139], v[184:187], v[48:51]
	v_mfma_f32_16x16x32_bf16 v[40:43], v[132:135], v[188:191], v[40:43]
	v_mfma_f32_16x16x32_bf16 v[40:43], v[136:139], v[192:195], v[40:43]
	v_mfma_f32_16x16x32_bf16 v[60:63], v[140:143], v[164:167], v[60:63]
	v_mfma_f32_16x16x32_bf16 v[60:63], v[144:147], v[168:171], v[60:63]
	v_mfma_f32_16x16x32_bf16 v[52:55], v[140:143], v[172:175], v[52:55]
	v_mfma_f32_16x16x32_bf16 v[52:55], v[144:147], v[176:179], v[52:55]
	v_mfma_f32_16x16x32_bf16 v[44:47], v[140:143], v[180:183], v[44:47]
	v_mfma_f32_16x16x32_bf16 v[44:47], v[144:147], v[184:187], v[44:47]
	v_mfma_f32_16x16x32_bf16 v[36:39], v[140:143], v[188:191], v[36:39]
	v_mfma_f32_16x16x32_bf16 v[36:39], v[144:147], v[192:195], v[36:39]
	v_mfma_f32_16x16x32_bf16 v[32:35], v[148:151], v[164:167], v[32:35]
	v_mfma_f32_16x16x32_bf16 v[32:35], v[152:155], v[168:171], v[32:35]
	v_mfma_f32_16x16x32_bf16 v[28:31], v[156:159], v[164:167], v[28:31]
	v_mfma_f32_16x16x32_bf16 v[28:31], v[160:163], v[168:171], v[28:31]
	v_mfma_f32_16x16x32_bf16 v[24:27], v[148:151], v[172:175], v[24:27]
	v_mfma_f32_16x16x32_bf16 v[24:27], v[152:155], v[176:179], v[24:27]
	v_mfma_f32_16x16x32_bf16 v[20:23], v[156:159], v[172:175], v[20:23]
	v_mfma_f32_16x16x32_bf16 v[20:23], v[160:163], v[176:179], v[20:23]
	v_mfma_f32_16x16x32_bf16 v[16:19], v[148:151], v[180:183], v[16:19]
	v_mfma_f32_16x16x32_bf16 v[16:19], v[152:155], v[184:187], v[16:19]
	v_mfma_f32_16x16x32_bf16 v[12:15], v[156:159], v[180:183], v[12:15]
	v_mfma_f32_16x16x32_bf16 v[12:15], v[160:163], v[184:187], v[12:15]
	v_mfma_f32_16x16x32_bf16 v[8:11], v[148:151], v[188:191], v[8:11]
	v_mfma_f32_16x16x32_bf16 v[8:11], v[152:155], v[192:195], v[8:11]
	v_mfma_f32_16x16x32_bf16 v[2:5], v[156:159], v[188:191], v[4:7]
	v_mfma_f32_16x16x32_bf16 v[2:5], v[160:163], v[192:195], v[2:5]
	s_barrier
	s_add_i32 s66, 0, 0x18000
	v_add_u32_e32 v0, s66, v228
	s_add_i32 s67, 0, 0x1c000
	ds_read_b128 v[132:135], v0
	ds_read_b128 v[136:139], v0 offset:1024
	ds_read_b128 v[140:143], v0 offset:2048
	ds_read_b128 v[144:147], v0 offset:3072
	v_add_u32_e32 v0, s67, v228
	ds_read_b128 v[148:151], v0
	ds_read_b128 v[152:155], v0 offset:1024
	ds_read_b128 v[156:159], v0 offset:2048
	ds_read_b128 v[160:163], v0 offset:3072
	s_mov_b32 m0, s46
	ds_read_b128 v[164:167], v230 offset:32768
	ds_read_b128 v[168:171], v230 offset:33792
	ds_read_b128 v[172:175], v230 offset:34816
	ds_read_b128 v[176:179], v230 offset:35840
	ds_read_b128 v[180:183], v230 offset:36864
	ds_read_b128 v[184:187], v230 offset:37888
	ds_read_b128 v[188:191], v230 offset:38912
	ds_read_b128 v[192:195], v230 offset:39936
	global_load_lds_dwordx4 v206, s[42:43]
	s_mov_b32 m0, s47
	s_nop 0
	global_load_lds_dwordx4 v202, s[42:43]
	s_add_u32 s42, s42, 0x80000
	s_addc_u32 s43, s43, 0
	s_mov_b32 m0, s48
	s_nop 0
	global_load_lds_dwordx4 v206, s[42:43]
	s_mov_b32 m0, s49
	s_nop 0
	global_load_lds_dwordx4 v202, s[42:43]
	s_waitcnt vmcnt(8)
	s_waitcnt lgkmcnt(0)
	s_barrier
	s_waitcnt lgkmcnt(0)
	v_mfma_f32_16x16x32_bf16 v[128:131], v[132:135], v[164:167], v[128:131]
	v_mfma_f32_16x16x32_bf16 v[128:131], v[136:139], v[168:171], v[128:131]
	v_mfma_f32_16x16x32_bf16 v[120:123], v[132:135], v[172:175], v[120:123]
	v_mfma_f32_16x16x32_bf16 v[120:123], v[136:139], v[176:179], v[120:123]
	v_mfma_f32_16x16x32_bf16 v[112:115], v[132:135], v[180:183], v[112:115]
	v_mfma_f32_16x16x32_bf16 v[112:115], v[136:139], v[184:187], v[112:115]
	v_mfma_f32_16x16x32_bf16 v[104:107], v[132:135], v[188:191], v[104:107]
	v_mfma_f32_16x16x32_bf16 v[104:107], v[136:139], v[192:195], v[104:107]
	v_mfma_f32_16x16x32_bf16 v[124:127], v[140:143], v[164:167], v[124:127]
	v_mfma_f32_16x16x32_bf16 v[124:127], v[144:147], v[168:171], v[124:127]
	v_mfma_f32_16x16x32_bf16 v[116:119], v[140:143], v[172:175], v[116:119]
	v_mfma_f32_16x16x32_bf16 v[116:119], v[144:147], v[176:179], v[116:119]
	v_mfma_f32_16x16x32_bf16 v[108:111], v[140:143], v[180:183], v[108:111]
	v_mfma_f32_16x16x32_bf16 v[108:111], v[144:147], v[184:187], v[108:111]
	v_mfma_f32_16x16x32_bf16 v[100:103], v[140:143], v[188:191], v[100:103]
	v_mfma_f32_16x16x32_bf16 v[100:103], v[144:147], v[192:195], v[100:103]
	v_mfma_f32_16x16x32_bf16 v[96:99], v[148:151], v[164:167], v[96:99]
	v_mfma_f32_16x16x32_bf16 v[96:99], v[152:155], v[168:171], v[96:99]
	v_mfma_f32_16x16x32_bf16 v[88:91], v[148:151], v[172:175], v[88:91]
	v_mfma_f32_16x16x32_bf16 v[88:91], v[152:155], v[176:179], v[88:91]
	v_mfma_f32_16x16x32_bf16 v[80:83], v[148:151], v[180:183], v[80:83]
	v_mfma_f32_16x16x32_bf16 v[80:83], v[152:155], v[184:187], v[80:83]
	v_mfma_f32_16x16x32_bf16 v[72:75], v[148:151], v[188:191], v[72:75]
	v_mfma_f32_16x16x32_bf16 v[72:75], v[152:155], v[192:195], v[72:75]
	v_mfma_f32_16x16x32_bf16 v[92:95], v[156:159], v[164:167], v[92:95]
	v_mfma_f32_16x16x32_bf16 v[92:95], v[160:163], v[168:171], v[92:95]
	v_mfma_f32_16x16x32_bf16 v[84:87], v[156:159], v[172:175], v[84:87]
	v_mfma_f32_16x16x32_bf16 v[84:87], v[160:163], v[176:179], v[84:87]
	v_mfma_f32_16x16x32_bf16 v[76:79], v[156:159], v[180:183], v[76:79]
	v_mfma_f32_16x16x32_bf16 v[76:79], v[160:163], v[184:187], v[76:79]
	v_mfma_f32_16x16x32_bf16 v[68:71], v[156:159], v[188:191], v[68:71]
	v_mfma_f32_16x16x32_bf16 v[68:71], v[160:163], v[192:195], v[68:71]
	s_barrier
	s_add_i32 s42, s66, s15
	s_add_u32 s98, s34, 0x80
	s_addc_u32 s99, s35, 0
	s_mov_b32 m0, s42
	ds_read_b128 v[164:167], v230 offset:49152
	ds_read_b128 v[168:171], v230 offset:50176
	ds_read_b128 v[172:175], v230 offset:51200
	ds_read_b128 v[176:179], v230 offset:52224
	ds_read_b128 v[180:183], v230 offset:53248
	ds_read_b128 v[184:187], v230 offset:54272
	ds_read_b128 v[188:191], v230 offset:55296
	ds_read_b128 v[192:195], v230 offset:56320
	global_load_lds_dwordx4 v204, s[98:99]
	s_add_i32 m0, s42, 0x2000
	s_add_u32 s34, s34, 0x80080
	s_addc_u32 s35, s35, 0
	s_add_i32 s42, s67, s15
	global_load_lds_dwordx4 v200, s[98:99]
	s_mov_b32 m0, s42
	s_nop 0
	global_load_lds_dwordx4 v204, s[34:35]
	s_add_i32 m0, s42, 0x2000
	s_nop 0
	global_load_lds_dwordx4 v200, s[34:35]
	s_waitcnt vmcnt(6)
	s_waitcnt lgkmcnt(0)
	s_barrier
	s_waitcnt lgkmcnt(0)
	v_mfma_f32_16x16x32_bf16 v[64:67], v[132:135], v[164:167], v[64:67]
	v_mfma_f32_16x16x32_bf16 v[64:67], v[136:139], v[168:171], v[64:67]
	v_mfma_f32_16x16x32_bf16 v[56:59], v[132:135], v[172:175], v[56:59]
	v_mfma_f32_16x16x32_bf16 v[56:59], v[136:139], v[176:179], v[56:59]
	v_mfma_f32_16x16x32_bf16 v[48:51], v[132:135], v[180:183], v[48:51]
	v_mfma_f32_16x16x32_bf16 v[48:51], v[136:139], v[184:187], v[48:51]
	v_mfma_f32_16x16x32_bf16 v[40:43], v[132:135], v[188:191], v[40:43]
	v_mfma_f32_16x16x32_bf16 v[40:43], v[136:139], v[192:195], v[40:43]
	v_mfma_f32_16x16x32_bf16 v[60:63], v[140:143], v[164:167], v[60:63]
	v_mfma_f32_16x16x32_bf16 v[60:63], v[144:147], v[168:171], v[60:63]
	v_mfma_f32_16x16x32_bf16 v[52:55], v[140:143], v[172:175], v[52:55]
	v_mfma_f32_16x16x32_bf16 v[52:55], v[144:147], v[176:179], v[52:55]
	v_mfma_f32_16x16x32_bf16 v[44:47], v[140:143], v[180:183], v[44:47]
	v_mfma_f32_16x16x32_bf16 v[44:47], v[144:147], v[184:187], v[44:47]
	v_mfma_f32_16x16x32_bf16 v[36:39], v[140:143], v[188:191], v[36:39]
	v_mfma_f32_16x16x32_bf16 v[36:39], v[144:147], v[192:195], v[36:39]
	v_mfma_f32_16x16x32_bf16 v[32:35], v[148:151], v[164:167], v[32:35]
	v_mfma_f32_16x16x32_bf16 v[32:35], v[152:155], v[168:171], v[32:35]
	v_mfma_f32_16x16x32_bf16 v[28:31], v[156:159], v[164:167], v[28:31]
	v_mfma_f32_16x16x32_bf16 v[28:31], v[160:163], v[168:171], v[28:31]
	v_mfma_f32_16x16x32_bf16 v[24:27], v[148:151], v[172:175], v[24:27]
	v_mfma_f32_16x16x32_bf16 v[24:27], v[152:155], v[176:179], v[24:27]
	v_mfma_f32_16x16x32_bf16 v[20:23], v[156:159], v[172:175], v[20:23]
	v_mfma_f32_16x16x32_bf16 v[20:23], v[160:163], v[176:179], v[20:23]
	v_mfma_f32_16x16x32_bf16 v[16:19], v[148:151], v[180:183], v[16:19]
	v_mfma_f32_16x16x32_bf16 v[16:19], v[152:155], v[184:187], v[16:19]
	v_mfma_f32_16x16x32_bf16 v[12:15], v[156:159], v[180:183], v[12:15]
	v_mfma_f32_16x16x32_bf16 v[12:15], v[160:163], v[184:187], v[12:15]
	v_mfma_f32_16x16x32_bf16 v[6:9], v[148:151], v[188:191], v[8:11]
	v_mfma_f32_16x16x32_bf16 v[8:11], v[152:155], v[192:195], v[6:9]
	v_mfma_f32_16x16x32_bf16 v[2:5], v[156:159], v[188:191], v[2:5]
	v_mfma_f32_16x16x32_bf16 v[4:7], v[160:163], v[192:195], v[2:5]
	s_barrier
	s_add_i32 s57, s57, 2
	s_add_u32 s30, s30, 0x100
	s_addc_u32 s31, s31, 0
	s_add_u32 s55, s55, 0x100
	s_addc_u32 s56, s56, 0
	s_cmp_gt_u32 s57, 29
	s_cbranch_scc0 .LBB0_577
	s_bitcmp1_b32 s60, 8
	s_cbranch_scc1 .Lepiprio_2
	s_setprio 1
.Lepiprio_2:
	s_and_b64 vcc, exec, s[20:21]
	s_cbranch_vccz .LBB0_580
	s_barrier

.LBB0_778:
	s_ashr_i32 s25, s24, 31
	s_lshl_b64 s[26:27], s[24:25], 20
	v_readlane_b32 s23, v253, 40
	s_add_u32 s26, s23, s26
	v_readlane_b32 s23, v253, 41
	s_addc_u32 s27, s23, s27
	s_and_b64 s[28:29], s[40:41], exec
	s_cselect_b32 s25, s27, s31
	s_cselect_b32 s53, s26, s30
	s_ashr_i32 s23, s22, 31
	s_lshl_b64 s[28:29], s[22:23], 20
	v_readlane_b32 s23, v253, 34
	s_add_u32 s28, s23, s28
	v_readlane_b32 s23, v253, 35
	s_addc_u32 s29, s23, s29
	s_and_b64 s[42:43], s[40:41], exec
	s_cselect_b32 s23, s29, s35
	s_cselect_b32 s54, s28, s34
	s_add_u32 s30, s30, 0x80080
	s_addc_u32 s31, s31, 0
	s_add_u32 s55, s34, 0x100
	v_mov_b64_e32 v[2:3], 0
	v_mov_b64_e32 v[4:5], 0
	v_mov_b64_e32 v[6:7], 0
	v_mov_b64_e32 v[8:9], 0
	v_mov_b64_e32 v[10:11], 0
	v_mov_b64_e32 v[12:13], 0
	v_mov_b64_e32 v[14:15], 0
	v_mov_b64_e32 v[16:17], 0
	v_mov_b64_e32 v[18:19], 0
	v_mov_b64_e32 v[20:21], 0
	v_mov_b64_e32 v[22:23], 0
	v_mov_b64_e32 v[24:25], 0
	v_mov_b64_e32 v[26:27], 0
	v_mov_b64_e32 v[28:29], 0
	v_mov_b64_e32 v[30:31], 0
	v_mov_b64_e32 v[32:33], 0
	v_mov_b64_e32 v[34:35], 0
	v_mov_b64_e32 v[36:37], 0
	v_mov_b64_e32 v[38:39], 0
	v_mov_b64_e32 v[40:41], 0
	v_mov_b64_e32 v[42:43], 0
	v_mov_b64_e32 v[44:45], 0
	v_mov_b64_e32 v[46:47], 0
	v_mov_b64_e32 v[48:49], 0
	v_mov_b64_e32 v[50:51], 0
	v_mov_b64_e32 v[52:53], 0
	v_mov_b64_e32 v[54:55], 0
	v_mov_b64_e32 v[56:57], 0
	v_mov_b64_e32 v[58:59], 0
	v_mov_b64_e32 v[60:61], 0
	v_mov_b64_e32 v[62:63], 0
	v_mov_b64_e32 v[64:65], 0
	v_mov_b64_e32 v[66:67], 0
	v_mov_b64_e32 v[68:69], 0
	v_mov_b64_e32 v[70:71], 0
	v_mov_b64_e32 v[72:73], 0
	v_mov_b64_e32 v[74:75], 0
	v_mov_b64_e32 v[76:77], 0
	v_mov_b64_e32 v[78:79], 0
	v_mov_b64_e32 v[80:81], 0
	v_mov_b64_e32 v[82:83], 0
	v_mov_b64_e32 v[84:85], 0
	v_mov_b64_e32 v[86:87], 0
	v_mov_b64_e32 v[88:89], 0
	v_mov_b64_e32 v[98:99], 0
	v_mov_b64_e32 v[100:101], 0
	v_mov_b64_e32 v[102:103], 0
	v_mov_b64_e32 v[104:105], 0
	v_mov_b64_e32 v[110:111], 0
	v_mov_b64_e32 v[112:113], 0
	v_mov_b64_e32 v[118:119], 0
	v_mov_b64_e32 v[120:121], 0
	v_mov_b64_e32 v[122:123], 0
	v_mov_b64_e32 v[124:125], 0
	v_mov_b64_e32 v[126:127], 0
	v_mov_b64_e32 v[128:129], 0
	v_mov_b64_e32 v[130:131], 0
	v_mov_b64_e32 v[132:133], 0
	v_mov_b64_e32 v[134:135], 0
	v_mov_b64_e32 v[136:137], 0
	v_mov_b64_e32 v[138:139], 0
	v_mov_b64_e32 v[140:141], 0
	v_mov_b64_e32 v[142:143], 0
	v_mov_b64_e32 v[144:145], 0
	s_addc_u32 s56, s35, 0
	s_mov_b32 s57, -2
	s_setprio 0
.LBB0_779:
	s_add_u32 s98, s30, 0xfff80000
	s_addc_u32 s99, s31, -1
	s_add_u32 s34, s30, 0xfff80080
	s_addc_u32 s35, s31, -1
	s_add_i32 s66, 0, 0x10000
	s_cmp_eq_u32 s57, 28
	s_cselect_b32 s43, s25, s35
	s_cselect_b32 s42, s53, s34
	s_cselect_b32 s35, s23, s56
	s_cselect_b32 s34, s54, s55
	s_add_i32 s73, 0, 0x14000
	v_add_u32_e32 v114, s66, v157
	v_add_u32_e32 v156, s73, v157
	ds_read_b128 v[90:93], v114
	ds_read_b128 v[94:97], v114 offset:1024
	ds_read_b128 v[106:109], v114 offset:2048
	ds_read_b128 v[114:117], v114 offset:3072
	ds_read_b128 v[162:165], v156
	ds_read_b128 v[166:169], v156 offset:1024
	ds_read_b128 v[170:173], v156 offset:2048
	ds_read_b128 v[174:177], v156 offset:3072
	s_mov_b32 m0, s50
	ds_read_b128 v[178:181], v161
	ds_read_b128 v[182:185], v161 offset:1024
	ds_read_b128 v[186:189], v161 offset:2048
	ds_read_b128 v[190:193], v161 offset:3072
	ds_read_b128 v[200:203], v161 offset:4096
	ds_read_b128 v[204:207], v161 offset:5120
	ds_read_b128 v[208:211], v161 offset:6144
	ds_read_b128 v[212:215], v161 offset:7168
	global_load_lds_dwordx4 v150, s[98:99]
	s_mov_b32 m0, s51
	s_nop 0
	global_load_lds_dwordx4 v148, s[98:99]
	s_add_i32 m0, s14, 0xc000
	s_nop 0
	global_load_lds_dwordx4 v152, s[30:31]
	s_add_i32 m0, s14, 0xe000
	s_nop 0
	global_load_lds_dwordx4 v154, s[30:31]
	s_waitcnt vmcnt(8)
	s_waitcnt lgkmcnt(0)
	s_barrier
	s_waitcnt lgkmcnt(0)
	v_mfma_i32_16x16x64_i8 v[142:145], v[90:93], v[178:181], v[142:145]
	v_mfma_i32_16x16x64_i8 v[142:145], v[94:97], v[182:185], v[142:145]
	v_mfma_i32_16x16x64_i8 v[126:129], v[90:93], v[186:189], v[126:129]
	v_mfma_i32_16x16x64_i8 v[126:129], v[94:97], v[190:193], v[126:129]
	v_mfma_i32_16x16x64_i8 v[102:105], v[90:93], v[200:203], v[102:105]
	v_mfma_i32_16x16x64_i8 v[102:105], v[94:97], v[204:207], v[102:105]
	v_mfma_i32_16x16x64_i8 v[78:81], v[90:93], v[208:211], v[78:81]
	v_mfma_i32_16x16x64_i8 v[78:81], v[94:97], v[212:215], v[78:81]
	v_mfma_i32_16x16x64_i8 v[138:141], v[106:109], v[178:181], v[138:141]
	v_mfma_i32_16x16x64_i8 v[138:141], v[114:117], v[182:185], v[138:141]
	v_mfma_i32_16x16x64_i8 v[122:125], v[106:109], v[186:189], v[122:125]
	v_mfma_i32_16x16x64_i8 v[122:125], v[114:117], v[190:193], v[122:125]
	v_mfma_i32_16x16x64_i8 v[98:101], v[106:109], v[200:203], v[98:101]
	v_mfma_i32_16x16x64_i8 v[98:101], v[114:117], v[204:207], v[98:101]
	v_mfma_i32_16x16x64_i8 v[74:77], v[106:109], v[208:211], v[74:77]
	v_mfma_i32_16x16x64_i8 v[74:77], v[114:117], v[212:215], v[74:77]
	v_mfma_i32_16x16x64_i8 v[134:137], v[162:165], v[178:181], v[134:137]
	v_mfma_i32_16x16x64_i8 v[134:137], v[166:169], v[182:185], v[134:137]
	v_mfma_i32_16x16x64_i8 v[118:121], v[162:165], v[186:189], v[118:121]
	v_mfma_i32_16x16x64_i8 v[118:121], v[166:169], v[190:193], v[118:121]
	v_mfma_i32_16x16x64_i8 v[86:89], v[162:165], v[200:203], v[86:89]
	v_mfma_i32_16x16x64_i8 v[86:89], v[166:169], v[204:207], v[86:89]
	v_mfma_i32_16x16x64_i8 v[70:73], v[162:165], v[208:211], v[70:73]
	v_mfma_i32_16x16x64_i8 v[70:73], v[166:169], v[212:215], v[70:73]
	v_mfma_i32_16x16x64_i8 v[130:133], v[170:173], v[178:181], v[130:133]
	v_mfma_i32_16x16x64_i8 v[130:133], v[174:177], v[182:185], v[130:133]
	v_mfma_i32_16x16x64_i8 v[110:113], v[170:173], v[186:189], v[110:113]
	v_mfma_i32_16x16x64_i8 v[110:113], v[174:177], v[190:193], v[110:113]
	v_mfma_i32_16x16x64_i8 v[82:85], v[170:173], v[200:203], v[82:85]
	v_mfma_i32_16x16x64_i8 v[82:85], v[174:177], v[204:207], v[82:85]
	v_mfma_i32_16x16x64_i8 v[66:69], v[170:173], v[208:211], v[66:69]
	v_mfma_i32_16x16x64_i8 v[66:69], v[174:177], v[212:215], v[66:69]
	s_barrier
	s_add_i32 s66, s66, s9
	s_mov_b32 m0, s66
	ds_read_b128 v[178:181], v161 offset:16384
	ds_read_b128 v[182:185], v161 offset:17408
	ds_read_b128 v[186:189], v161 offset:18432
	ds_read_b128 v[190:193], v161 offset:19456
	ds_read_b128 v[200:203], v161 offset:20480
	ds_read_b128 v[204:207], v161 offset:21504
	ds_read_b128 v[208:211], v161 offset:22528
	ds_read_b128 v[212:215], v161 offset:23552
	global_load_lds_dwordx4 v0, s[34:35]
	s_add_i32 m0, s66, 0x2000
	s_add_u32 s66, s34, 0x80000
	s_addc_u32 s67, s35, 0
	s_add_i32 s73, s73, s9
	global_load_lds_dwordx4 v146, s[34:35]
	s_mov_b32 m0, s73
	s_nop 0
	global_load_lds_dwordx4 v0, s[66:67]
	s_add_i32 m0, s73, 0x2000
	s_nop 0
	global_load_lds_dwordx4 v146, s[66:67]
	s_waitcnt vmcnt(6)
	s_waitcnt lgkmcnt(0)
	s_barrier
	s_waitcnt lgkmcnt(0)
	v_mfma_i32_16x16x64_i8 v[62:65], v[90:93], v[178:181], v[62:65]
	v_mfma_i32_16x16x64_i8 v[62:65], v[94:97], v[182:185], v[62:65]
	v_mfma_i32_16x16x64_i8 v[46:49], v[90:93], v[186:189], v[46:49]
	v_mfma_i32_16x16x64_i8 v[46:49], v[94:97], v[190:193], v[46:49]
	v_mfma_i32_16x16x64_i8 v[30:33], v[90:93], v[200:203], v[30:33]
	v_mfma_i32_16x16x64_i8 v[30:33], v[94:97], v[204:207], v[30:33]
	v_mfma_i32_16x16x64_i8 v[14:17], v[90:93], v[208:211], v[14:17]
	v_mfma_i32_16x16x64_i8 v[14:17], v[94:97], v[212:215], v[14:17]
	v_mfma_i32_16x16x64_i8 v[58:61], v[106:109], v[178:181], v[58:61]
	v_mfma_i32_16x16x64_i8 v[58:61], v[114:117], v[182:185], v[58:61]
	v_mfma_i32_16x16x64_i8 v[42:45], v[106:109], v[186:189], v[42:45]
	v_mfma_i32_16x16x64_i8 v[42:45], v[114:117], v[190:193], v[42:45]
	v_mfma_i32_16x16x64_i8 v[26:29], v[106:109], v[200:203], v[26:29]
	v_mfma_i32_16x16x64_i8 v[26:29], v[114:117], v[204:207], v[26:29]
	v_mfma_i32_16x16x64_i8 v[10:13], v[106:109], v[208:211], v[10:13]
	v_mfma_i32_16x16x64_i8 v[10:13], v[114:117], v[212:215], v[10:13]
	v_mfma_i32_16x16x64_i8 v[54:57], v[162:165], v[178:181], v[54:57]
	v_mfma_i32_16x16x64_i8 v[54:57], v[166:169], v[182:185], v[54:57]
	v_mfma_i32_16x16x64_i8 v[38:41], v[162:165], v[186:189], v[38:41]
	v_mfma_i32_16x16x64_i8 v[38:41], v[166:169], v[190:193], v[38:41]
	v_mfma_i32_16x16x64_i8 v[22:25], v[162:165], v[200:203], v[22:25]
	v_mfma_i32_16x16x64_i8 v[22:25], v[166:169], v[204:207], v[22:25]
	v_mfma_i32_16x16x64_i8 v[6:9], v[162:165], v[208:211], v[6:9]
	v_mfma_i32_16x16x64_i8 v[6:9], v[166:169], v[212:215], v[6:9]
	v_mfma_i32_16x16x64_i8 v[50:53], v[170:173], v[178:181], v[50:53]
	v_mfma_i32_16x16x64_i8 v[50:53], v[174:177], v[182:185], v[50:53]
	v_mfma_i32_16x16x64_i8 v[34:37], v[170:173], v[186:189], v[34:37]
	v_mfma_i32_16x16x64_i8 v[34:37], v[174:177], v[190:193], v[34:37]
	v_mfma_i32_16x16x64_i8 v[18:21], v[170:173], v[200:203], v[18:21]
	v_mfma_i32_16x16x64_i8 v[18:21], v[174:177], v[204:207], v[18:21]
	v_mfma_i32_16x16x64_i8 v[2:5], v[170:173], v[208:211], v[2:5]
	v_mfma_i32_16x16x64_i8 v[2:5], v[174:177], v[212:215], v[2:5]
	s_barrier
	s_add_i32 s66, 0, 0x18000
	s_add_i32 s67, 0, 0x1c000
	v_add_u32_e32 v114, s66, v157
	v_add_u32_e32 v156, s67, v157
	ds_read_b128 v[90:93], v114
	ds_read_b128 v[94:97], v114 offset:1024
	ds_read_b128 v[106:109], v114 offset:2048
	ds_read_b128 v[114:117], v114 offset:3072
	ds_read_b128 v[162:165], v156
	ds_read_b128 v[166:169], v156 offset:1024
	ds_read_b128 v[170:173], v156 offset:2048
	ds_read_b128 v[174:177], v156 offset:3072
	s_mov_b32 m0, s14
	ds_read_b128 v[178:181], v161 offset:32768
	ds_read_b128 v[182:185], v161 offset:33792
	ds_read_b128 v[186:189], v161 offset:34816
	ds_read_b128 v[190:193], v161 offset:35840
	ds_read_b128 v[200:203], v161 offset:36864
	ds_read_b128 v[204:207], v161 offset:37888
	ds_read_b128 v[208:211], v161 offset:38912
	ds_read_b128 v[212:215], v161 offset:39936
	global_load_lds_dwordx4 v150, s[42:43]
	s_mov_b32 m0, s15
	s_nop 0
	global_load_lds_dwordx4 v148, s[42:43]
	s_add_u32 s42, s42, 0x80000
	s_addc_u32 s43, s43, 0
	s_mov_b32 m0, s46
	s_nop 0
	global_load_lds_dwordx4 v150, s[42:43]
	s_mov_b32 m0, s47
	s_nop 0
	global_load_lds_dwordx4 v148, s[42:43]
	s_waitcnt vmcnt(8)
	s_waitcnt lgkmcnt(0)
	s_barrier
	s_waitcnt lgkmcnt(0)
	v_mfma_i32_16x16x64_i8 v[142:145], v[90:93], v[178:181], v[142:145]
	v_mfma_i32_16x16x64_i8 v[142:145], v[94:97], v[182:185], v[142:145]
	v_mfma_i32_16x16x64_i8 v[126:129], v[90:93], v[186:189], v[126:129]
	v_mfma_i32_16x16x64_i8 v[126:129], v[94:97], v[190:193], v[126:129]
	v_mfma_i32_16x16x64_i8 v[102:105], v[90:93], v[200:203], v[102:105]
	v_mfma_i32_16x16x64_i8 v[102:105], v[94:97], v[204:207], v[102:105]
	v_mfma_i32_16x16x64_i8 v[78:81], v[90:93], v[208:211], v[78:81]
	v_mfma_i32_16x16x64_i8 v[78:81], v[94:97], v[212:215], v[78:81]
	v_mfma_i32_16x16x64_i8 v[138:141], v[106:109], v[178:181], v[138:141]
	v_mfma_i32_16x16x64_i8 v[138:141], v[114:117], v[182:185], v[138:141]
	v_mfma_i32_16x16x64_i8 v[122:125], v[106:109], v[186:189], v[122:125]
	v_mfma_i32_16x16x64_i8 v[122:125], v[114:117], v[190:193], v[122:125]
	v_mfma_i32_16x16x64_i8 v[98:101], v[106:109], v[200:203], v[98:101]
	v_mfma_i32_16x16x64_i8 v[98:101], v[114:117], v[204:207], v[98:101]
	v_mfma_i32_16x16x64_i8 v[74:77], v[106:109], v[208:211], v[74:77]
	v_mfma_i32_16x16x64_i8 v[74:77], v[114:117], v[212:215], v[74:77]
	v_mfma_i32_16x16x64_i8 v[134:137], v[162:165], v[178:181], v[134:137]
	v_mfma_i32_16x16x64_i8 v[134:137], v[166:169], v[182:185], v[134:137]
	v_mfma_i32_16x16x64_i8 v[118:121], v[162:165], v[186:189], v[118:121]
	v_mfma_i32_16x16x64_i8 v[118:121], v[166:169], v[190:193], v[118:121]
	v_mfma_i32_16x16x64_i8 v[86:89], v[162:165], v[200:203], v[86:89]
	v_mfma_i32_16x16x64_i8 v[86:89], v[166:169], v[204:207], v[86:89]
	v_mfma_i32_16x16x64_i8 v[70:73], v[162:165], v[208:211], v[70:73]
	v_mfma_i32_16x16x64_i8 v[70:73], v[166:169], v[212:215], v[70:73]
	v_mfma_i32_16x16x64_i8 v[130:133], v[170:173], v[178:181], v[130:133]
	v_mfma_i32_16x16x64_i8 v[130:133], v[174:177], v[182:185], v[130:133]
	v_mfma_i32_16x16x64_i8 v[110:113], v[170:173], v[186:189], v[110:113]
	v_mfma_i32_16x16x64_i8 v[110:113], v[174:177], v[190:193], v[110:113]
	v_mfma_i32_16x16x64_i8 v[82:85], v[170:173], v[200:203], v[82:85]
	v_mfma_i32_16x16x64_i8 v[82:85], v[174:177], v[204:207], v[82:85]
	v_mfma_i32_16x16x64_i8 v[66:69], v[170:173], v[208:211], v[66:69]
	v_mfma_i32_16x16x64_i8 v[66:69], v[174:177], v[212:215], v[66:69]
	s_barrier
	s_add_u32 s98, s34, 0x80
	s_addc_u32 s99, s35, 0
	s_add_i32 s42, s66, s9
	s_mov_b32 m0, s42
	ds_read_b128 v[178:181], v161 offset:49152
	ds_read_b128 v[182:185], v161 offset:50176
	ds_read_b128 v[186:189], v161 offset:51200
	ds_read_b128 v[190:193], v161 offset:52224
	ds_read_b128 v[200:203], v161 offset:53248
	ds_read_b128 v[204:207], v161 offset:54272
	ds_read_b128 v[208:211], v161 offset:55296
	ds_read_b128 v[212:215], v161 offset:56320
	global_load_lds_dwordx4 v0, s[98:99]
	s_add_i32 m0, s42, 0x2000
	s_add_u32 s34, s34, 0x80080
	s_addc_u32 s35, s35, 0
	s_add_i32 s42, s67, s9
	global_load_lds_dwordx4 v146, s[98:99]
	s_mov_b32 m0, s42
	s_nop 0
	global_load_lds_dwordx4 v0, s[34:35]
	s_add_i32 m0, s42, 0x2000
	s_nop 0
	global_load_lds_dwordx4 v146, s[34:35]
	s_waitcnt vmcnt(6)
	s_waitcnt lgkmcnt(0)
	s_barrier
	s_waitcnt lgkmcnt(0)
	v_mfma_i32_16x16x64_i8 v[62:65], v[90:93], v[178:181], v[62:65]
	v_mfma_i32_16x16x64_i8 v[62:65], v[94:97], v[182:185], v[62:65]
	v_mfma_i32_16x16x64_i8 v[46:49], v[90:93], v[186:189], v[46:49]
	v_mfma_i32_16x16x64_i8 v[46:49], v[94:97], v[190:193], v[46:49]
	v_mfma_i32_16x16x64_i8 v[30:33], v[90:93], v[200:203], v[30:33]
	v_mfma_i32_16x16x64_i8 v[30:33], v[94:97], v[204:207], v[30:33]
	v_mfma_i32_16x16x64_i8 v[14:17], v[90:93], v[208:211], v[14:17]
	v_mfma_i32_16x16x64_i8 v[14:17], v[94:97], v[212:215], v[14:17]
	v_mfma_i32_16x16x64_i8 v[58:61], v[106:109], v[178:181], v[58:61]
	v_mfma_i32_16x16x64_i8 v[58:61], v[114:117], v[182:185], v[58:61]
	v_mfma_i32_16x16x64_i8 v[42:45], v[106:109], v[186:189], v[42:45]
	v_mfma_i32_16x16x64_i8 v[42:45], v[114:117], v[190:193], v[42:45]
	v_mfma_i32_16x16x64_i8 v[26:29], v[106:109], v[200:203], v[26:29]
	v_mfma_i32_16x16x64_i8 v[26:29], v[114:117], v[204:207], v[26:29]
	v_mfma_i32_16x16x64_i8 v[10:13], v[106:109], v[208:211], v[10:13]
	v_mfma_i32_16x16x64_i8 v[10:13], v[114:117], v[212:215], v[10:13]
	v_mfma_i32_16x16x64_i8 v[54:57], v[162:165], v[178:181], v[54:57]
	v_mfma_i32_16x16x64_i8 v[54:57], v[166:169], v[182:185], v[54:57]
	v_mfma_i32_16x16x64_i8 v[38:41], v[162:165], v[186:189], v[38:41]
	v_mfma_i32_16x16x64_i8 v[38:41], v[166:169], v[190:193], v[38:41]
	v_mfma_i32_16x16x64_i8 v[22:25], v[162:165], v[200:203], v[22:25]
	v_mfma_i32_16x16x64_i8 v[22:25], v[166:169], v[204:207], v[22:25]
	v_mfma_i32_16x16x64_i8 v[6:9], v[162:165], v[208:211], v[6:9]
	v_mfma_i32_16x16x64_i8 v[6:9], v[166:169], v[212:215], v[6:9]
	v_mfma_i32_16x16x64_i8 v[50:53], v[170:173], v[178:181], v[50:53]
	v_mfma_i32_16x16x64_i8 v[50:53], v[174:177], v[182:185], v[50:53]
	v_mfma_i32_16x16x64_i8 v[34:37], v[170:173], v[186:189], v[34:37]
	v_mfma_i32_16x16x64_i8 v[34:37], v[174:177], v[190:193], v[34:37]
	v_mfma_i32_16x16x64_i8 v[18:21], v[170:173], v[200:203], v[18:21]
	v_mfma_i32_16x16x64_i8 v[18:21], v[174:177], v[204:207], v[18:21]
	v_mfma_i32_16x16x64_i8 v[2:5], v[170:173], v[208:211], v[2:5]
	v_mfma_i32_16x16x64_i8 v[2:5], v[174:177], v[212:215], v[2:5]
	s_barrier
	s_add_i32 s57, s57, 2
	s_add_u32 s30, s30, 0x100
	s_addc_u32 s31, s31, 0
	s_add_u32 s55, s55, 0x100
	s_addc_u32 s56, s56, 0
	s_cmp_gt_u32 s57, 29
	s_cbranch_scc0 .LBB0_779
	s_bitcmp1_b32 s60, 8
	s_cbranch_scc1 .Lepiprio_3
	s_setprio 1
.Lepiprio_3:
	s_and_b64 vcc, exec, s[20:21]
	s_mov_b32 s54, 0x5c401000
	s_cbranch_vccz .LBB0_782
	s_barrier

.LBB0_800:
	s_ashr_i32 s25, s24, 31
	s_lshl_b64 s[26:27], s[24:25], 21
	s_add_u32 s26, s70, s26
	s_addc_u32 s27, s71, s27
	s_and_b64 s[28:29], s[38:39], exec
	s_cselect_b32 s25, s27, s31
	s_cselect_b32 s49, s26, s30
	s_ashr_i32 s23, s22, 31
	s_lshl_b64 s[28:29], s[22:23], 21
	v_readlane_b32 s23, v253, 52
	s_add_u32 s28, s23, s28
	v_readlane_b32 s23, v253, 53
	s_addc_u32 s29, s23, s29
	s_and_b64 s[40:41], s[38:39], exec
	s_cselect_b32 s23, s29, s35
	s_cselect_b32 s50, s28, s34
	s_add_u32 s30, s30, 0x100080
	s_addc_u32 s31, s31, 0
	s_add_u32 s51, s34, 0x100
	v_mov_b64_e32 v[2:3], 0
	v_mov_b64_e32 v[4:5], 0
	v_mov_b64_e32 v[6:7], 0
	v_mov_b64_e32 v[8:9], 0
	v_mov_b64_e32 v[10:11], 0
	v_mov_b64_e32 v[12:13], 0
	v_mov_b64_e32 v[14:15], 0
	v_mov_b64_e32 v[16:17], 0
	v_mov_b64_e32 v[18:19], 0
	v_mov_b64_e32 v[20:21], 0
	v_mov_b64_e32 v[22:23], 0
	v_mov_b64_e32 v[24:25], 0
	v_mov_b64_e32 v[26:27], 0
	v_mov_b64_e32 v[28:29], 0
	v_mov_b64_e32 v[30:31], 0
	v_mov_b64_e32 v[32:33], 0
	v_mov_b64_e32 v[34:35], 0
	v_mov_b64_e32 v[36:37], 0
	v_mov_b64_e32 v[38:39], 0
	v_mov_b64_e32 v[40:41], 0
	v_mov_b64_e32 v[42:43], 0
	v_mov_b64_e32 v[44:45], 0
	v_mov_b64_e32 v[46:47], 0
	v_mov_b64_e32 v[48:49], 0
	v_mov_b64_e32 v[50:51], 0
	v_mov_b64_e32 v[52:53], 0
	v_mov_b64_e32 v[54:55], 0
	v_mov_b64_e32 v[56:57], 0
	v_mov_b64_e32 v[58:59], 0
	v_mov_b64_e32 v[60:61], 0
	v_mov_b64_e32 v[62:63], 0
	v_mov_b64_e32 v[64:65], 0
	v_mov_b64_e32 v[66:67], 0
	v_mov_b64_e32 v[68:69], 0
	v_mov_b64_e32 v[70:71], 0
	v_mov_b64_e32 v[72:73], 0
	v_mov_b64_e32 v[74:75], 0
	v_mov_b64_e32 v[76:77], 0
	v_mov_b64_e32 v[78:79], 0
	v_mov_b64_e32 v[80:81], 0
	v_mov_b64_e32 v[82:83], 0
	v_mov_b64_e32 v[84:85], 0
	v_mov_b64_e32 v[86:87], 0
	v_mov_b64_e32 v[88:89], 0
	v_mov_b64_e32 v[90:91], 0
	v_mov_b64_e32 v[92:93], 0
	v_mov_b64_e32 v[94:95], 0
	v_mov_b64_e32 v[96:97], 0
	v_mov_b64_e32 v[98:99], 0
	v_mov_b64_e32 v[100:101], 0
	v_mov_b64_e32 v[102:103], 0
	v_mov_b64_e32 v[104:105], 0
	v_mov_b64_e32 v[106:107], 0
	v_mov_b64_e32 v[108:109], 0
	v_mov_b64_e32 v[110:111], 0
	v_mov_b64_e32 v[112:113], 0
	v_mov_b64_e32 v[114:115], 0
	v_mov_b64_e32 v[116:117], 0
	v_mov_b64_e32 v[118:119], 0
	v_mov_b64_e32 v[120:121], 0
	v_mov_b64_e32 v[122:123], 0
	v_mov_b64_e32 v[124:125], 0
	v_mov_b64_e32 v[126:127], 0
	v_mov_b64_e32 v[128:129], 0
	s_addc_u32 s52, s35, 0
	s_mov_b32 s53, -2
	s_setprio 0
.LBB0_801:
	s_add_u32 s98, s30, 0xfff00000
	s_addc_u32 s99, s31, -1
	s_add_u32 s34, s30, 0xfff00080
	s_addc_u32 s35, s31, -1
	s_add_i32 s54, 0, 0x10000
	s_cmp_eq_u32 s53, 60
	s_cselect_b32 s41, s25, s35
	s_cselect_b32 s40, s49, s34
	s_cselect_b32 s35, s23, s52
	s_cselect_b32 s34, s50, s51
	s_add_i32 s56, 0, 0x14000
	v_add_u32_e32 v156, s54, v141
	v_add_u32_e32 v172, s56, v141
	ds_read_b128 v[144:147], v156
	ds_read_b128 v[148:151], v156 offset:1024
	ds_read_b128 v[152:155], v156 offset:2048
	ds_read_b128 v[156:159], v156 offset:3072
	ds_read_b128 v[160:163], v172
	ds_read_b128 v[164:167], v172 offset:1024
	ds_read_b128 v[168:171], v172 offset:2048
	ds_read_b128 v[172:175], v172 offset:3072
	s_mov_b32 m0, s42
	ds_read_b128 v[176:179], v143
	ds_read_b128 v[180:183], v143 offset:1024
	ds_read_b128 v[184:187], v143 offset:2048
	ds_read_b128 v[188:191], v143 offset:3072
	ds_read_b128 v[192:195], v143 offset:4096
	ds_read_b128 v[200:203], v143 offset:5120
	ds_read_b128 v[204:207], v143 offset:6144
	ds_read_b128 v[208:211], v143 offset:7168
	global_load_lds_dwordx4 v134, s[98:99]
	s_mov_b32 m0, s43
	s_nop 0
	global_load_lds_dwordx4 v132, s[98:99]
	s_add_i32 m0, s14, 0xc000
	s_nop 0
	global_load_lds_dwordx4 v136, s[30:31]
	s_add_i32 m0, s14, 0xe000
	s_nop 0
	global_load_lds_dwordx4 v138, s[30:31]
	s_waitcnt vmcnt(8)
	s_waitcnt lgkmcnt(0)
	s_barrier
	s_waitcnt lgkmcnt(0)
	v_mfma_f32_16x16x32_bf16 v[126:129], v[144:147], v[176:179], v[126:129]
	v_mfma_f32_16x16x32_bf16 v[126:129], v[148:151], v[180:183], v[126:129]
	v_mfma_f32_16x16x32_bf16 v[118:121], v[144:147], v[184:187], v[118:121]
	v_mfma_f32_16x16x32_bf16 v[118:121], v[148:151], v[188:191], v[118:121]
	v_mfma_f32_16x16x32_bf16 v[102:105], v[144:147], v[192:195], v[102:105]
	v_mfma_f32_16x16x32_bf16 v[102:105], v[148:151], v[200:203], v[102:105]
	v_mfma_f32_16x16x32_bf16 v[86:89], v[144:147], v[204:207], v[86:89]
	v_mfma_f32_16x16x32_bf16 v[86:89], v[148:151], v[208:211], v[86:89]
	v_mfma_f32_16x16x32_bf16 v[122:125], v[152:155], v[176:179], v[122:125]
	v_mfma_f32_16x16x32_bf16 v[122:125], v[156:159], v[180:183], v[122:125]
	v_mfma_f32_16x16x32_bf16 v[114:117], v[152:155], v[184:187], v[114:117]
	v_mfma_f32_16x16x32_bf16 v[114:117], v[156:159], v[188:191], v[114:117]
	v_mfma_f32_16x16x32_bf16 v[98:101], v[152:155], v[192:195], v[98:101]
	v_mfma_f32_16x16x32_bf16 v[98:101], v[156:159], v[200:203], v[98:101]
	v_mfma_f32_16x16x32_bf16 v[82:85], v[152:155], v[204:207], v[82:85]
	v_mfma_f32_16x16x32_bf16 v[82:85], v[156:159], v[208:211], v[82:85]
	v_mfma_f32_16x16x32_bf16 v[110:113], v[160:163], v[176:179], v[110:113]
	v_mfma_f32_16x16x32_bf16 v[110:113], v[164:167], v[180:183], v[110:113]
	v_mfma_f32_16x16x32_bf16 v[94:97], v[160:163], v[184:187], v[94:97]
	v_mfma_f32_16x16x32_bf16 v[94:97], v[164:167], v[188:191], v[94:97]
	v_mfma_f32_16x16x32_bf16 v[78:81], v[160:163], v[192:195], v[78:81]
	v_mfma_f32_16x16x32_bf16 v[78:81], v[164:167], v[200:203], v[78:81]
	v_mfma_f32_16x16x32_bf16 v[70:73], v[160:163], v[204:207], v[70:73]
	v_mfma_f32_16x16x32_bf16 v[70:73], v[164:167], v[208:211], v[70:73]
	v_mfma_f32_16x16x32_bf16 v[106:109], v[168:171], v[176:179], v[106:109]
	v_mfma_f32_16x16x32_bf16 v[106:109], v[172:175], v[180:183], v[106:109]
	v_mfma_f32_16x16x32_bf16 v[90:93], v[168:171], v[184:187], v[90:93]
	v_mfma_f32_16x16x32_bf16 v[90:93], v[172:175], v[188:191], v[90:93]
	v_mfma_f32_16x16x32_bf16 v[74:77], v[168:171], v[192:195], v[74:77]
	v_mfma_f32_16x16x32_bf16 v[74:77], v[172:175], v[200:203], v[74:77]
	v_mfma_f32_16x16x32_bf16 v[66:69], v[168:171], v[204:207], v[66:69]
	v_mfma_f32_16x16x32_bf16 v[66:69], v[172:175], v[208:211], v[66:69]
	s_barrier
	s_add_i32 s54, s54, s9
	s_mov_b32 m0, s54
	ds_read_b128 v[176:179], v143 offset:16384
	ds_read_b128 v[180:183], v143 offset:17408
	ds_read_b128 v[184:187], v143 offset:18432
	ds_read_b128 v[188:191], v143 offset:19456
	ds_read_b128 v[192:195], v143 offset:20480
	ds_read_b128 v[200:203], v143 offset:21504
	ds_read_b128 v[204:207], v143 offset:22528
	ds_read_b128 v[208:211], v143 offset:23552
	global_load_lds_dwordx4 v0, s[34:35]
	s_add_i32 m0, s54, 0x2000
	s_add_u32 s54, s34, 0x100000
	s_addc_u32 s55, s35, 0
	s_add_i32 s56, s56, s9
	global_load_lds_dwordx4 v130, s[34:35]
	s_mov_b32 m0, s56
	s_nop 0
	global_load_lds_dwordx4 v0, s[54:55]
	s_add_i32 m0, s56, 0x2000
	s_nop 0
	global_load_lds_dwordx4 v130, s[54:55]
	s_waitcnt vmcnt(6)
	s_waitcnt lgkmcnt(0)
	s_barrier
	s_waitcnt lgkmcnt(0)
	v_mfma_f32_16x16x32_bf16 v[62:65], v[144:147], v[176:179], v[62:65]
	v_mfma_f32_16x16x32_bf16 v[62:65], v[148:151], v[180:183], v[62:65]
	v_mfma_f32_16x16x32_bf16 v[54:57], v[144:147], v[184:187], v[54:57]
	v_mfma_f32_16x16x32_bf16 v[54:57], v[148:151], v[188:191], v[54:57]
	v_mfma_f32_16x16x32_bf16 v[38:41], v[144:147], v[192:195], v[38:41]
	v_mfma_f32_16x16x32_bf16 v[38:41], v[148:151], v[200:203], v[38:41]
	v_mfma_f32_16x16x32_bf16 v[22:25], v[144:147], v[204:207], v[22:25]
	v_mfma_f32_16x16x32_bf16 v[22:25], v[148:151], v[208:211], v[22:25]
	v_mfma_f32_16x16x32_bf16 v[58:61], v[152:155], v[176:179], v[58:61]
	v_mfma_f32_16x16x32_bf16 v[58:61], v[156:159], v[180:183], v[58:61]
	v_mfma_f32_16x16x32_bf16 v[50:53], v[152:155], v[184:187], v[50:53]
	v_mfma_f32_16x16x32_bf16 v[50:53], v[156:159], v[188:191], v[50:53]
	v_mfma_f32_16x16x32_bf16 v[34:37], v[152:155], v[192:195], v[34:37]
	v_mfma_f32_16x16x32_bf16 v[34:37], v[156:159], v[200:203], v[34:37]
	v_mfma_f32_16x16x32_bf16 v[18:21], v[152:155], v[204:207], v[18:21]
	v_mfma_f32_16x16x32_bf16 v[18:21], v[156:159], v[208:211], v[18:21]
	v_mfma_f32_16x16x32_bf16 v[46:49], v[160:163], v[176:179], v[46:49]
	v_mfma_f32_16x16x32_bf16 v[46:49], v[164:167], v[180:183], v[46:49]
	v_mfma_f32_16x16x32_bf16 v[30:33], v[160:163], v[184:187], v[30:33]
	v_mfma_f32_16x16x32_bf16 v[30:33], v[164:167], v[188:191], v[30:33]
	v_mfma_f32_16x16x32_bf16 v[14:17], v[160:163], v[192:195], v[14:17]
	v_mfma_f32_16x16x32_bf16 v[14:17], v[164:167], v[200:203], v[14:17]
	v_mfma_f32_16x16x32_bf16 v[6:9], v[160:163], v[204:207], v[6:9]
	v_mfma_f32_16x16x32_bf16 v[6:9], v[164:167], v[208:211], v[6:9]
	v_mfma_f32_16x16x32_bf16 v[42:45], v[168:171], v[176:179], v[42:45]
	v_mfma_f32_16x16x32_bf16 v[42:45], v[172:175], v[180:183], v[42:45]
	v_mfma_f32_16x16x32_bf16 v[26:29], v[168:171], v[184:187], v[26:29]
	v_mfma_f32_16x16x32_bf16 v[26:29], v[172:175], v[188:191], v[26:29]
	v_mfma_f32_16x16x32_bf16 v[10:13], v[168:171], v[192:195], v[10:13]
	v_mfma_f32_16x16x32_bf16 v[10:13], v[172:175], v[200:203], v[10:13]
	v_mfma_f32_16x16x32_bf16 v[2:5], v[168:171], v[204:207], v[2:5]
	v_mfma_f32_16x16x32_bf16 v[2:5], v[172:175], v[208:211], v[2:5]
	s_barrier
	s_add_i32 s54, 0, 0x18000
	s_add_i32 s55, 0, 0x1c000
	v_add_u32_e32 v156, s54, v141
	v_add_u32_e32 v172, s55, v141
	ds_read_b128 v[144:147], v156
	ds_read_b128 v[148:151], v156 offset:1024
	ds_read_b128 v[152:155], v156 offset:2048
	ds_read_b128 v[156:159], v156 offset:3072
	ds_read_b128 v[160:163], v172
	ds_read_b128 v[164:167], v172 offset:1024
	ds_read_b128 v[168:171], v172 offset:2048
	ds_read_b128 v[172:175], v172 offset:3072
	s_mov_b32 m0, s14
	ds_read_b128 v[176:179], v143 offset:32768
	ds_read_b128 v[180:183], v143 offset:33792
	ds_read_b128 v[184:187], v143 offset:34816
	ds_read_b128 v[188:191], v143 offset:35840
	ds_read_b128 v[192:195], v143 offset:36864
	ds_read_b128 v[200:203], v143 offset:37888
	ds_read_b128 v[204:207], v143 offset:38912
	ds_read_b128 v[208:211], v143 offset:39936
	global_load_lds_dwordx4 v134, s[40:41]
	s_mov_b32 m0, s15
	s_nop 0
	global_load_lds_dwordx4 v132, s[40:41]
	s_add_u32 s40, s40, 0x100000
	s_addc_u32 s41, s41, 0
	s_mov_b32 m0, s18
	s_nop 0
	global_load_lds_dwordx4 v134, s[40:41]
	s_mov_b32 m0, s19
	s_nop 0
	global_load_lds_dwordx4 v132, s[40:41]
	s_waitcnt vmcnt(8)
	s_waitcnt lgkmcnt(0)
	s_barrier
	s_waitcnt lgkmcnt(0)
	v_mfma_f32_16x16x32_bf16 v[126:129], v[144:147], v[176:179], v[126:129]
	v_mfma_f32_16x16x32_bf16 v[126:129], v[148:151], v[180:183], v[126:129]
	v_mfma_f32_16x16x32_bf16 v[118:121], v[144:147], v[184:187], v[118:121]
	v_mfma_f32_16x16x32_bf16 v[118:121], v[148:151], v[188:191], v[118:121]
	v_mfma_f32_16x16x32_bf16 v[102:105], v[144:147], v[192:195], v[102:105]
	v_mfma_f32_16x16x32_bf16 v[102:105], v[148:151], v[200:203], v[102:105]
	v_mfma_f32_16x16x32_bf16 v[86:89], v[144:147], v[204:207], v[86:89]
	v_mfma_f32_16x16x32_bf16 v[86:89], v[148:151], v[208:211], v[86:89]
	v_mfma_f32_16x16x32_bf16 v[122:125], v[152:155], v[176:179], v[122:125]
	v_mfma_f32_16x16x32_bf16 v[122:125], v[156:159], v[180:183], v[122:125]
	v_mfma_f32_16x16x32_bf16 v[114:117], v[152:155], v[184:187], v[114:117]
	v_mfma_f32_16x16x32_bf16 v[114:117], v[156:159], v[188:191], v[114:117]
	v_mfma_f32_16x16x32_bf16 v[98:101], v[152:155], v[192:195], v[98:101]
	v_mfma_f32_16x16x32_bf16 v[98:101], v[156:159], v[200:203], v[98:101]
	v_mfma_f32_16x16x32_bf16 v[82:85], v[152:155], v[204:207], v[82:85]
	v_mfma_f32_16x16x32_bf16 v[82:85], v[156:159], v[208:211], v[82:85]
	v_mfma_f32_16x16x32_bf16 v[110:113], v[160:163], v[176:179], v[110:113]
	v_mfma_f32_16x16x32_bf16 v[110:113], v[164:167], v[180:183], v[110:113]
	v_mfma_f32_16x16x32_bf16 v[94:97], v[160:163], v[184:187], v[94:97]
	v_mfma_f32_16x16x32_bf16 v[94:97], v[164:167], v[188:191], v[94:97]
	v_mfma_f32_16x16x32_bf16 v[78:81], v[160:163], v[192:195], v[78:81]
	v_mfma_f32_16x16x32_bf16 v[78:81], v[164:167], v[200:203], v[78:81]
	v_mfma_f32_16x16x32_bf16 v[70:73], v[160:163], v[204:207], v[70:73]
	v_mfma_f32_16x16x32_bf16 v[70:73], v[164:167], v[208:211], v[70:73]
	v_mfma_f32_16x16x32_bf16 v[106:109], v[168:171], v[176:179], v[106:109]
	v_mfma_f32_16x16x32_bf16 v[106:109], v[172:175], v[180:183], v[106:109]
	v_mfma_f32_16x16x32_bf16 v[90:93], v[168:171], v[184:187], v[90:93]
	v_mfma_f32_16x16x32_bf16 v[90:93], v[172:175], v[188:191], v[90:93]
	v_mfma_f32_16x16x32_bf16 v[74:77], v[168:171], v[192:195], v[74:77]
	v_mfma_f32_16x16x32_bf16 v[74:77], v[172:175], v[200:203], v[74:77]
	v_mfma_f32_16x16x32_bf16 v[66:69], v[168:171], v[204:207], v[66:69]
	v_mfma_f32_16x16x32_bf16 v[66:69], v[172:175], v[208:211], v[66:69]
	s_barrier
	s_add_u32 s98, s34, 0x80
	s_addc_u32 s99, s35, 0
	s_add_i32 s40, s54, s9
	s_mov_b32 m0, s40
	ds_read_b128 v[176:179], v143 offset:49152
	ds_read_b128 v[180:183], v143 offset:50176
	ds_read_b128 v[184:187], v143 offset:51200
	ds_read_b128 v[188:191], v143 offset:52224
	ds_read_b128 v[192:195], v143 offset:53248
	ds_read_b128 v[200:203], v143 offset:54272
	ds_read_b128 v[204:207], v143 offset:55296
	ds_read_b128 v[208:211], v143 offset:56320
	global_load_lds_dwordx4 v0, s[98:99]
	s_add_i32 m0, s40, 0x2000
	s_add_u32 s34, s34, 0x100080
	s_addc_u32 s35, s35, 0
	s_add_i32 s40, s55, s9
	global_load_lds_dwordx4 v130, s[98:99]
	s_mov_b32 m0, s40
	s_nop 0
	global_load_lds_dwordx4 v0, s[34:35]
	s_add_i32 m0, s40, 0x2000
	s_nop 0
	global_load_lds_dwordx4 v130, s[34:35]
	s_waitcnt vmcnt(6)
	s_waitcnt lgkmcnt(0)
	s_barrier
	s_waitcnt lgkmcnt(0)
	v_mfma_f32_16x16x32_bf16 v[62:65], v[144:147], v[176:179], v[62:65]
	v_mfma_f32_16x16x32_bf16 v[62:65], v[148:151], v[180:183], v[62:65]
	v_mfma_f32_16x16x32_bf16 v[54:57], v[144:147], v[184:187], v[54:57]
	v_mfma_f32_16x16x32_bf16 v[54:57], v[148:151], v[188:191], v[54:57]
	v_mfma_f32_16x16x32_bf16 v[38:41], v[144:147], v[192:195], v[38:41]
	v_mfma_f32_16x16x32_bf16 v[38:41], v[148:151], v[200:203], v[38:41]
	v_mfma_f32_16x16x32_bf16 v[22:25], v[144:147], v[204:207], v[22:25]
	v_mfma_f32_16x16x32_bf16 v[22:25], v[148:151], v[208:211], v[22:25]
	v_mfma_f32_16x16x32_bf16 v[58:61], v[152:155], v[176:179], v[58:61]
	v_mfma_f32_16x16x32_bf16 v[58:61], v[156:159], v[180:183], v[58:61]
	v_mfma_f32_16x16x32_bf16 v[50:53], v[152:155], v[184:187], v[50:53]
	v_mfma_f32_16x16x32_bf16 v[50:53], v[156:159], v[188:191], v[50:53]
	v_mfma_f32_16x16x32_bf16 v[34:37], v[152:155], v[192:195], v[34:37]
	v_mfma_f32_16x16x32_bf16 v[34:37], v[156:159], v[200:203], v[34:37]
	v_mfma_f32_16x16x32_bf16 v[18:21], v[152:155], v[204:207], v[18:21]
	v_mfma_f32_16x16x32_bf16 v[18:21], v[156:159], v[208:211], v[18:21]
	v_mfma_f32_16x16x32_bf16 v[46:49], v[160:163], v[176:179], v[46:49]
	v_mfma_f32_16x16x32_bf16 v[46:49], v[164:167], v[180:183], v[46:49]
	v_mfma_f32_16x16x32_bf16 v[30:33], v[160:163], v[184:187], v[30:33]
	v_mfma_f32_16x16x32_bf16 v[30:33], v[164:167], v[188:191], v[30:33]
	v_mfma_f32_16x16x32_bf16 v[14:17], v[160:163], v[192:195], v[14:17]
	v_mfma_f32_16x16x32_bf16 v[14:17], v[164:167], v[200:203], v[14:17]
	v_mfma_f32_16x16x32_bf16 v[6:9], v[160:163], v[204:207], v[6:9]
	v_mfma_f32_16x16x32_bf16 v[6:9], v[164:167], v[208:211], v[6:9]
	v_mfma_f32_16x16x32_bf16 v[42:45], v[168:171], v[176:179], v[42:45]
	v_mfma_f32_16x16x32_bf16 v[42:45], v[172:175], v[180:183], v[42:45]
	v_mfma_f32_16x16x32_bf16 v[26:29], v[168:171], v[184:187], v[26:29]
	v_mfma_f32_16x16x32_bf16 v[26:29], v[172:175], v[188:191], v[26:29]
	v_mfma_f32_16x16x32_bf16 v[10:13], v[168:171], v[192:195], v[10:13]
	v_mfma_f32_16x16x32_bf16 v[10:13], v[172:175], v[200:203], v[10:13]
	v_mfma_f32_16x16x32_bf16 v[2:5], v[168:171], v[204:207], v[2:5]
	v_mfma_f32_16x16x32_bf16 v[2:5], v[172:175], v[208:211], v[2:5]
	s_barrier
	s_add_i32 s53, s53, 2
	s_add_u32 s30, s30, 0x100
	s_addc_u32 s31, s31, 0
	s_add_u32 s51, s51, 0x100
	s_addc_u32 s52, s52, 0
	s_cmp_gt_u32 s53, 61
	s_cbranch_scc0 .LBB0_801
	s_bitcmp1_b32 s60, 8
	s_cbranch_scc1 .Lepiprio_4
	s_setprio 1
